# static priority: trailing half-workgroup (waves 4-7) at s_setprio 1 for each GEMM K-loop, all per-segment flips deleted (on s8p)
# baseline (speedup 1.0000x reference)
.LBB0_321:
	s_ashr_i32 s39, s38, 31
	s_lshl_b64 s[44:45], s[38:39], 19
	s_add_u32 s56, s22, s44
	s_addc_u32 s57, s23, s45
	s_and_b64 s[0:1], s[0:1], exec
	s_cselect_b32 s31, s57, s71
	s_cselect_b32 s39, s56, s70
	s_add_u32 s0, s70, 0x40080
	s_addc_u32 s1, s71, 0
	s_add_u32 s91, s68, 0x100
	v_mov_b32_e32 v2, 0
	s_addc_u32 s92, s69, 0
	s_mov_b32 s93, -2
	v_mov_b32_e32 v3, v2
	v_mov_b32_e32 v4, v2
	v_mov_b32_e32 v5, v2
	v_mov_b32_e32 v6, v2
	v_mov_b32_e32 v7, v2
	v_mov_b32_e32 v8, v2
	v_mov_b32_e32 v9, v2
	v_mov_b32_e32 v10, v2
	v_mov_b32_e32 v11, v2
	v_mov_b32_e32 v12, v2
	v_mov_b32_e32 v13, v2
	v_mov_b32_e32 v18, v2
	v_mov_b32_e32 v19, v2
	v_mov_b32_e32 v20, v2
	v_mov_b32_e32 v21, v2
	v_mov_b32_e32 v26, v2
	v_mov_b32_e32 v27, v2
	v_mov_b32_e32 v28, v2
	v_mov_b32_e32 v29, v2
	v_mov_b32_e32 v34, v2
	v_mov_b32_e32 v35, v2
	v_mov_b32_e32 v36, v2
	v_mov_b32_e32 v37, v2
	v_mov_b32_e32 v42, v2
	v_mov_b32_e32 v43, v2
	v_mov_b32_e32 v44, v2
	v_mov_b32_e32 v45, v2
	v_mov_b32_e32 v50, v2
	v_mov_b32_e32 v51, v2
	v_mov_b32_e32 v52, v2
	v_mov_b32_e32 v53, v2
	v_mov_b32_e32 v14, v2
	s_waitcnt lgkmcnt(0)
	v_mov_b32_e32 v15, v2
	v_mov_b32_e32 v16, v2
	v_mov_b32_e32 v17, v2
	v_mov_b32_e32 v22, v2
	v_mov_b32_e32 v23, v2
	v_mov_b32_e32 v24, v2
	v_mov_b32_e32 v25, v2
	v_mov_b32_e32 v30, v2
	v_mov_b32_e32 v31, v2
	v_mov_b32_e32 v32, v2
	v_mov_b32_e32 v33, v2
	v_mov_b32_e32 v38, v2
	v_mov_b32_e32 v39, v2
	v_mov_b32_e32 v40, v2
	v_mov_b32_e32 v41, v2
	v_mov_b32_e32 v46, v2
	v_mov_b32_e32 v47, v2
	v_mov_b32_e32 v48, v2
	v_mov_b32_e32 v49, v2
	v_mov_b32_e32 v54, v2
	v_mov_b32_e32 v55, v2
	v_mov_b32_e32 v56, v2
	v_mov_b32_e32 v57, v2
	v_mov_b32_e32 v58, v2
	v_mov_b32_e32 v59, v2
	v_mov_b32_e32 v60, v2
	v_mov_b32_e32 v61, v2
	v_mov_b32_e32 v62, v2
	v_mov_b32_e32 v63, v2
	v_mov_b32_e32 v64, v2
	v_mov_b32_e32 v65, v2
	v_mov_b32_e32 v66, v2
	v_mov_b32_e32 v67, v2
	v_mov_b32_e32 v68, v2
	v_mov_b32_e32 v69, v2
	v_mov_b32_e32 v70, v2
	v_mov_b32_e32 v71, v2
	v_mov_b32_e32 v72, v2
	v_mov_b32_e32 v73, v2
	v_mov_b32_e32 v74, v2
	v_mov_b32_e32 v75, v2
	v_mov_b32_e32 v76, v2
	v_mov_b32_e32 v77, v2
	v_mov_b32_e32 v82, v2
	v_mov_b32_e32 v83, v2
	v_mov_b32_e32 v84, v2
	v_mov_b32_e32 v85, v2
	v_mov_b32_e32 v90, v2
	v_mov_b32_e32 v91, v2
	v_mov_b32_e32 v92, v2
	v_mov_b32_e32 v93, v2
	v_mov_b32_e32 v100, v2
	v_mov_b32_e32 v101, v2
	v_mov_b32_e32 v102, v2
	v_mov_b32_e32 v103, v2
	v_mov_b32_e32 v108, v2
	v_mov_b32_e32 v109, v2
	v_mov_b32_e32 v110, v2
	v_mov_b32_e32 v111, v2
	v_mov_b32_e32 v116, v2
	v_mov_b32_e32 v117, v2
	v_mov_b32_e32 v118, v2
	v_mov_b32_e32 v119, v2
	v_mov_b32_e32 v78, v2
	v_mov_b32_e32 v79, v2
	v_mov_b32_e32 v80, v2
	v_mov_b32_e32 v81, v2
	v_mov_b32_e32 v86, v2
	v_mov_b32_e32 v87, v2
	v_mov_b32_e32 v88, v2
	v_mov_b32_e32 v89, v2
	v_mov_b32_e32 v94, v2
	v_mov_b32_e32 v95, v2
	v_mov_b32_e32 v96, v2
	v_mov_b32_e32 v97, v2
	v_mov_b32_e32 v104, v2
	v_mov_b32_e32 v105, v2
	v_mov_b32_e32 v106, v2
	v_mov_b32_e32 v107, v2
	v_mov_b32_e32 v112, v2
	v_mov_b32_e32 v113, v2
	v_mov_b32_e32 v114, v2
	v_mov_b32_e32 v115, v2
	v_mov_b32_e32 v120, v2
	v_mov_b32_e32 v121, v2
	v_mov_b32_e32 v122, v2
	v_mov_b32_e32 v123, v2
	v_mov_b32_e32 v124, v2
	v_mov_b32_e32 v125, v2
	v_mov_b32_e32 v126, v2
	v_mov_b32_e32 v127, v2
	v_mov_b32_e32 v128, v2
	v_mov_b32_e32 v129, v2
	v_mov_b32_e32 v130, v2
	v_mov_b32_e32 v131, v2
	s_bitcmp1_b32 s77, 12
	s_cbranch_scc0 .Lmy_sp_g1
	s_setprio 1
.Lmy_sp_g1:
.LBB0_322:
	s_add_u32 s4, s0, 0xfffc0080
	s_addc_u32 s5, s1, -1
	s_add_i32 s44, 0, 0x10000
	s_cmp_eq_u32 s93, 12
	s_cselect_b32 s71, s31, s5
	s_cselect_b32 s70, s39, s4
	s_cselect_b32 s69, s41, s92
	s_cselect_b32 s68, s40, s91
	s_add_i32 s4, 0, 0x14000
	v_add_u32_e32 v144, s44, v175
	v_add_u32_e32 v168, s4, v175
	ds_read_b128 v[132:135], v144
	ds_read_b128 v[136:139], v144 offset:1024
	ds_read_b128 v[140:143], v144 offset:2048
	ds_read_b128 v[144:147], v144 offset:3072
	ds_read_b128 v[156:159], v168
	ds_read_b128 v[160:163], v168 offset:1024
	ds_read_b128 v[164:167], v168 offset:2048
	ds_read_b128 v[180:183], v168 offset:3072
	s_add_i32 s94, s77, 0
	v_lshl_add_u64 v[168:169], s[0:1], 0, v[98:99]
	s_add_i32 m0, s94, 0xc000
	ds_read_b128 v[184:187], v179
	ds_read_b128 v[188:191], v179 offset:1024
	ds_read_b128 v[192:195], v179 offset:2048
	ds_read_b128 v[204:207], v179 offset:3072
	ds_read_b128 v[208:211], v179 offset:4096
	ds_read_b128 v[212:215], v179 offset:5120
	ds_read_b128 v[216:219], v179 offset:6144
	ds_read_b128 v[220:223], v179 offset:7168
	global_load_lds_dwordx4 v[168:169], off
	v_lshl_add_u64 v[168:169], s[0:1], 0, v[150:151]
	s_add_i32 m0, s94, 0xe000
	s_nop 0
	global_load_lds_dwordx4 v[168:169], off
	s_cmp_eq_u32 s100, 1
	s_cbranch_scc1 .Lmy_sk1
	s_waitcnt vmcnt(8)
.Lmy_sk1:
	s_waitcnt lgkmcnt(0)
	s_barrier
	v_mfma_f32_16x16x32_bf16 v[128:131], v[132:135], v[184:187], v[128:131]
	v_mfma_f32_16x16x32_bf16 v[124:127], v[140:143], v[184:187], v[124:127]
	v_mfma_f32_16x16x32_bf16 v[120:123], v[132:135], v[192:195], v[120:123]
	v_mfma_f32_16x16x32_bf16 v[112:115], v[140:143], v[192:195], v[112:115]
	v_mfma_f32_16x16x32_bf16 v[104:107], v[132:135], v[208:211], v[104:107]
	v_mfma_f32_16x16x32_bf16 v[94:97], v[140:143], v[208:211], v[94:97]
	v_mfma_f32_16x16x32_bf16 v[86:89], v[132:135], v[216:219], v[86:89]
	v_mfma_f32_16x16x32_bf16 v[78:81], v[140:143], v[216:219], v[78:81]
	v_mfma_f32_16x16x32_bf16 v[128:131], v[136:139], v[188:191], v[128:131]
	v_mfma_f32_16x16x32_bf16 v[124:127], v[144:147], v[188:191], v[124:127]
	v_mfma_f32_16x16x32_bf16 v[120:123], v[136:139], v[204:207], v[120:123]
	v_mfma_f32_16x16x32_bf16 v[112:115], v[144:147], v[204:207], v[112:115]
	v_mfma_f32_16x16x32_bf16 v[104:107], v[136:139], v[212:215], v[104:107]
	v_mfma_f32_16x16x32_bf16 v[94:97], v[144:147], v[212:215], v[94:97]
	v_mfma_f32_16x16x32_bf16 v[86:89], v[136:139], v[220:223], v[86:89]
	v_mfma_f32_16x16x32_bf16 v[78:81], v[144:147], v[220:223], v[78:81]
	v_mfma_f32_16x16x32_bf16 v[116:119], v[156:159], v[184:187], v[116:119]
	v_mfma_f32_16x16x32_bf16 v[108:111], v[164:167], v[184:187], v[108:111]
	v_mfma_f32_16x16x32_bf16 v[100:103], v[156:159], v[192:195], v[100:103]
	v_mfma_f32_16x16x32_bf16 v[90:93], v[164:167], v[192:195], v[90:93]
	v_mfma_f32_16x16x32_bf16 v[82:85], v[156:159], v[208:211], v[82:85]
	v_mfma_f32_16x16x32_bf16 v[74:77], v[164:167], v[208:211], v[74:77]
	v_mfma_f32_16x16x32_bf16 v[70:73], v[156:159], v[216:219], v[70:73]
	v_mfma_f32_16x16x32_bf16 v[66:69], v[164:167], v[216:219], v[66:69]
	v_mfma_f32_16x16x32_bf16 v[116:119], v[160:163], v[188:191], v[116:119]
	v_mfma_f32_16x16x32_bf16 v[108:111], v[180:183], v[188:191], v[108:111]
	v_mfma_f32_16x16x32_bf16 v[100:103], v[160:163], v[204:207], v[100:103]
	v_mfma_f32_16x16x32_bf16 v[90:93], v[180:183], v[204:207], v[90:93]
	v_mfma_f32_16x16x32_bf16 v[82:85], v[160:163], v[212:215], v[82:85]
	v_mfma_f32_16x16x32_bf16 v[74:77], v[180:183], v[212:215], v[74:77]
	v_mfma_f32_16x16x32_bf16 v[70:73], v[160:163], v[220:223], v[70:73]
	v_mfma_f32_16x16x32_bf16 v[66:69], v[180:183], v[220:223], v[66:69]
	s_barrier
	s_add_i32 s5, s44, s77
	v_lshl_add_u64 v[168:169], s[68:69], 0, v[148:149]
	s_mov_b32 m0, s5
	ds_read_b128 v[184:187], v179 offset:16384
	ds_read_b128 v[188:191], v179 offset:17408
	ds_read_b128 v[192:195], v179 offset:18432
	ds_read_b128 v[204:207], v179 offset:19456
	ds_read_b128 v[208:211], v179 offset:20480
	ds_read_b128 v[212:215], v179 offset:21504
	ds_read_b128 v[216:219], v179 offset:22528
	ds_read_b128 v[220:223], v179 offset:23552
	global_load_lds_dwordx4 v[168:169], off
	s_add_i32 m0, s5, 0x2000
	s_add_u32 s44, s68, 0x40000
	v_lshl_add_u64 v[172:173], s[68:69], 0, v[152:153]
	s_addc_u32 s45, s69, 0
	s_add_i32 s4, s4, s77
	global_load_lds_dwordx4 v[172:173], off
	v_lshl_add_u64 v[176:177], s[44:45], 0, v[148:149]
	s_mov_b32 m0, s4
	v_lshl_add_u64 v[200:201], s[70:71], 0, v[150:151]
	global_load_lds_dwordx4 v[176:177], off
	v_lshl_add_u64 v[176:177], s[44:45], 0, v[152:153]
	s_add_i32 m0, s4, 0x2000
	s_nop 0
	global_load_lds_dwordx4 v[176:177], off
	v_lshl_add_u64 v[176:177], s[70:71], 0, v[98:99]
	s_mov_b32 m0, s94
	s_nop 0
	global_load_lds_dwordx4 v[176:177], off
	s_add_i32 m0, s94, 0x2000
	s_nop 0
	global_load_lds_dwordx4 v[200:201], off
	s_cmp_eq_u32 s100, 1
	s_cbranch_scc1 .Lmy_sk2
	s_waitcnt vmcnt(8)
.Lmy_sk2:
	s_waitcnt lgkmcnt(0)
	s_barrier
	v_mfma_f32_16x16x32_bf16 v[62:65], v[132:135], v[184:187], v[62:65]
	v_mfma_f32_16x16x32_bf16 v[58:61], v[140:143], v[184:187], v[58:61]
	v_mfma_f32_16x16x32_bf16 v[54:57], v[132:135], v[192:195], v[54:57]
	v_mfma_f32_16x16x32_bf16 v[46:49], v[140:143], v[192:195], v[46:49]
	v_mfma_f32_16x16x32_bf16 v[38:41], v[132:135], v[208:211], v[38:41]
	v_mfma_f32_16x16x32_bf16 v[30:33], v[140:143], v[208:211], v[30:33]
	v_mfma_f32_16x16x32_bf16 v[22:25], v[132:135], v[216:219], v[22:25]
	v_mfma_f32_16x16x32_bf16 v[14:17], v[140:143], v[216:219], v[14:17]
	v_mfma_f32_16x16x32_bf16 v[62:65], v[136:139], v[188:191], v[62:65]
	v_mfma_f32_16x16x32_bf16 v[58:61], v[144:147], v[188:191], v[58:61]
	v_mfma_f32_16x16x32_bf16 v[54:57], v[136:139], v[204:207], v[54:57]
	v_mfma_f32_16x16x32_bf16 v[46:49], v[144:147], v[204:207], v[46:49]
	v_mfma_f32_16x16x32_bf16 v[38:41], v[136:139], v[212:215], v[38:41]
	v_mfma_f32_16x16x32_bf16 v[30:33], v[144:147], v[212:215], v[30:33]
	v_mfma_f32_16x16x32_bf16 v[22:25], v[136:139], v[220:223], v[22:25]
	v_mfma_f32_16x16x32_bf16 v[14:17], v[144:147], v[220:223], v[14:17]
	v_mfma_f32_16x16x32_bf16 v[50:53], v[156:159], v[184:187], v[50:53]
	v_mfma_f32_16x16x32_bf16 v[42:45], v[164:167], v[184:187], v[42:45]
	v_mfma_f32_16x16x32_bf16 v[34:37], v[156:159], v[192:195], v[34:37]
	v_mfma_f32_16x16x32_bf16 v[26:29], v[164:167], v[192:195], v[26:29]
	v_mfma_f32_16x16x32_bf16 v[18:21], v[156:159], v[208:211], v[18:21]
	v_mfma_f32_16x16x32_bf16 v[10:13], v[164:167], v[208:211], v[10:13]
	v_mfma_f32_16x16x32_bf16 v[6:9], v[156:159], v[216:219], v[6:9]
	v_mfma_f32_16x16x32_bf16 v[2:5], v[164:167], v[216:219], v[2:5]
	v_mfma_f32_16x16x32_bf16 v[50:53], v[160:163], v[188:191], v[50:53]
	v_mfma_f32_16x16x32_bf16 v[42:45], v[180:183], v[188:191], v[42:45]
	v_mfma_f32_16x16x32_bf16 v[34:37], v[160:163], v[204:207], v[34:37]
	v_mfma_f32_16x16x32_bf16 v[26:29], v[180:183], v[204:207], v[26:29]
	v_mfma_f32_16x16x32_bf16 v[18:21], v[160:163], v[212:215], v[18:21]
	v_mfma_f32_16x16x32_bf16 v[10:13], v[180:183], v[212:215], v[10:13]
	v_mfma_f32_16x16x32_bf16 v[6:9], v[160:163], v[220:223], v[6:9]
	v_mfma_f32_16x16x32_bf16 v[2:5], v[180:183], v[220:223], v[2:5]
	s_barrier
	s_add_i32 s4, 0, 0x18000
	s_add_i32 s5, 0, 0x1c000
	v_add_u32_e32 v144, s4, v175
	v_add_u32_e32 v170, s5, v175
	ds_read_b128 v[132:135], v144
	ds_read_b128 v[136:139], v144 offset:1024
	ds_read_b128 v[140:143], v144 offset:2048
	ds_read_b128 v[144:147], v144 offset:3072
	ds_read_b128 v[156:159], v170
	ds_read_b128 v[160:163], v170 offset:1024
	ds_read_b128 v[164:167], v170 offset:2048
	ds_read_b128 v[180:183], v170 offset:3072
	s_add_u32 s44, s70, 0x40000
	s_addc_u32 s45, s71, 0
	v_lshl_add_u64 v[202:203], s[44:45], 0, v[98:99]
	s_add_i32 m0, s94, 0x4000
	ds_read_b128 v[184:187], v179 offset:32768
	ds_read_b128 v[188:191], v179 offset:33792
	ds_read_b128 v[192:195], v179 offset:34816
	ds_read_b128 v[204:207], v179 offset:35840
	ds_read_b128 v[208:211], v179 offset:36864
	ds_read_b128 v[212:215], v179 offset:37888
	ds_read_b128 v[216:219], v179 offset:38912
	ds_read_b128 v[220:223], v179 offset:39936
	global_load_lds_dwordx4 v[202:203], off
	v_lshl_add_u64 v[202:203], s[44:45], 0, v[150:151]
	s_add_i32 m0, s94, 0x6000
	s_nop 0
	global_load_lds_dwordx4 v[202:203], off
	s_waitcnt vmcnt(8)
	s_waitcnt lgkmcnt(0)
	s_barrier
	v_mfma_f32_16x16x32_bf16 v[128:131], v[132:135], v[184:187], v[128:131]
	v_mfma_f32_16x16x32_bf16 v[124:127], v[140:143], v[184:187], v[124:127]
	v_mfma_f32_16x16x32_bf16 v[120:123], v[132:135], v[192:195], v[120:123]
	v_mfma_f32_16x16x32_bf16 v[112:115], v[140:143], v[192:195], v[112:115]
	v_mfma_f32_16x16x32_bf16 v[104:107], v[132:135], v[208:211], v[104:107]
	v_mfma_f32_16x16x32_bf16 v[94:97], v[140:143], v[208:211], v[94:97]
	v_mfma_f32_16x16x32_bf16 v[86:89], v[132:135], v[216:219], v[86:89]
	v_mfma_f32_16x16x32_bf16 v[78:81], v[140:143], v[216:219], v[78:81]
	v_mfma_f32_16x16x32_bf16 v[128:131], v[136:139], v[188:191], v[128:131]
	v_mfma_f32_16x16x32_bf16 v[124:127], v[144:147], v[188:191], v[124:127]
	v_mfma_f32_16x16x32_bf16 v[120:123], v[136:139], v[204:207], v[120:123]
	v_mfma_f32_16x16x32_bf16 v[112:115], v[144:147], v[204:207], v[112:115]
	v_mfma_f32_16x16x32_bf16 v[104:107], v[136:139], v[212:215], v[104:107]
	v_mfma_f32_16x16x32_bf16 v[94:97], v[144:147], v[212:215], v[94:97]
	v_mfma_f32_16x16x32_bf16 v[86:89], v[136:139], v[220:223], v[86:89]
	v_mfma_f32_16x16x32_bf16 v[78:81], v[144:147], v[220:223], v[78:81]
	v_mfma_f32_16x16x32_bf16 v[116:119], v[156:159], v[184:187], v[116:119]
	v_mfma_f32_16x16x32_bf16 v[108:111], v[164:167], v[184:187], v[108:111]
	v_mfma_f32_16x16x32_bf16 v[100:103], v[156:159], v[192:195], v[100:103]
	v_mfma_f32_16x16x32_bf16 v[90:93], v[164:167], v[192:195], v[90:93]
	v_mfma_f32_16x16x32_bf16 v[82:85], v[156:159], v[208:211], v[82:85]
	v_mfma_f32_16x16x32_bf16 v[74:77], v[164:167], v[208:211], v[74:77]
	v_mfma_f32_16x16x32_bf16 v[70:73], v[156:159], v[216:219], v[70:73]
	v_mfma_f32_16x16x32_bf16 v[66:69], v[164:167], v[216:219], v[66:69]
	v_mfma_f32_16x16x32_bf16 v[116:119], v[160:163], v[188:191], v[116:119]
	v_mfma_f32_16x16x32_bf16 v[108:111], v[180:183], v[188:191], v[108:111]
	v_mfma_f32_16x16x32_bf16 v[100:103], v[160:163], v[204:207], v[100:103]
	v_mfma_f32_16x16x32_bf16 v[90:93], v[180:183], v[204:207], v[90:93]
	v_mfma_f32_16x16x32_bf16 v[82:85], v[160:163], v[212:215], v[82:85]
	v_mfma_f32_16x16x32_bf16 v[74:77], v[180:183], v[212:215], v[74:77]
	v_mfma_f32_16x16x32_bf16 v[70:73], v[160:163], v[220:223], v[70:73]
	v_mfma_f32_16x16x32_bf16 v[66:69], v[180:183], v[220:223], v[66:69]
	s_barrier
	s_add_i32 s4, s4, s77
	v_lshl_add_u64 v[168:169], v[168:169], 0, s[42:43]
	s_mov_b32 m0, s4
	ds_read_b128 v[184:187], v179 offset:49152
	ds_read_b128 v[188:191], v179 offset:50176
	ds_read_b128 v[192:195], v179 offset:51200
	ds_read_b128 v[204:207], v179 offset:52224
	ds_read_b128 v[208:211], v179 offset:53248
	ds_read_b128 v[212:215], v179 offset:54272
	ds_read_b128 v[216:219], v179 offset:55296
	ds_read_b128 v[220:223], v179 offset:56320
	global_load_lds_dwordx4 v[168:169], off
	s_add_i32 m0, s4, 0x2000
	s_add_u32 s44, s68, 0x40080
	v_lshl_add_u64 v[168:169], v[172:173], 0, s[42:43]
	s_addc_u32 s45, s69, 0
	s_add_i32 s4, s5, s77
	global_load_lds_dwordx4 v[168:169], off
	v_lshl_add_u64 v[168:169], s[44:45], 0, v[148:149]
	s_mov_b32 m0, s4
	s_nop 0
	global_load_lds_dwordx4 v[168:169], off
	v_lshl_add_u64 v[168:169], s[44:45], 0, v[152:153]
	s_add_i32 m0, s4, 0x2000
	s_nop 0
	global_load_lds_dwordx4 v[168:169], off
	v_lshl_add_u64 v[168:169], v[176:177], 0, s[42:43]
	s_add_i32 m0, s94, 0x8000
	s_nop 0
	global_load_lds_dwordx4 v[168:169], off
	v_lshl_add_u64 v[168:169], v[200:201], 0, s[42:43]
	s_add_i32 m0, s94, 0xa000
	s_nop 0
	global_load_lds_dwordx4 v[168:169], off
	s_waitcnt vmcnt(8)
	s_waitcnt lgkmcnt(0)
	s_barrier
	v_mfma_f32_16x16x32_bf16 v[62:65], v[132:135], v[184:187], v[62:65]
	v_mfma_f32_16x16x32_bf16 v[58:61], v[140:143], v[184:187], v[58:61]
	v_mfma_f32_16x16x32_bf16 v[54:57], v[132:135], v[192:195], v[54:57]
	v_mfma_f32_16x16x32_bf16 v[46:49], v[140:143], v[192:195], v[46:49]
	v_mfma_f32_16x16x32_bf16 v[38:41], v[132:135], v[208:211], v[38:41]
	v_mfma_f32_16x16x32_bf16 v[30:33], v[140:143], v[208:211], v[30:33]
	v_mfma_f32_16x16x32_bf16 v[22:25], v[132:135], v[216:219], v[22:25]
	v_mfma_f32_16x16x32_bf16 v[14:17], v[140:143], v[216:219], v[14:17]
	v_mfma_f32_16x16x32_bf16 v[62:65], v[136:139], v[188:191], v[62:65]
	v_mfma_f32_16x16x32_bf16 v[58:61], v[144:147], v[188:191], v[58:61]
	v_mfma_f32_16x16x32_bf16 v[54:57], v[136:139], v[204:207], v[54:57]
	v_mfma_f32_16x16x32_bf16 v[46:49], v[144:147], v[204:207], v[46:49]
	v_mfma_f32_16x16x32_bf16 v[38:41], v[136:139], v[212:215], v[38:41]
	v_mfma_f32_16x16x32_bf16 v[30:33], v[144:147], v[212:215], v[30:33]
	v_mfma_f32_16x16x32_bf16 v[22:25], v[136:139], v[220:223], v[22:25]
	v_mfma_f32_16x16x32_bf16 v[14:17], v[144:147], v[220:223], v[14:17]
	v_mfma_f32_16x16x32_bf16 v[50:53], v[156:159], v[184:187], v[50:53]
	v_mfma_f32_16x16x32_bf16 v[42:45], v[164:167], v[184:187], v[42:45]
	v_mfma_f32_16x16x32_bf16 v[34:37], v[156:159], v[192:195], v[34:37]
	v_mfma_f32_16x16x32_bf16 v[26:29], v[164:167], v[192:195], v[26:29]
	v_mfma_f32_16x16x32_bf16 v[18:21], v[156:159], v[208:211], v[18:21]
	v_mfma_f32_16x16x32_bf16 v[10:13], v[164:167], v[208:211], v[10:13]
	v_mfma_f32_16x16x32_bf16 v[6:9], v[156:159], v[216:219], v[6:9]
	v_mfma_f32_16x16x32_bf16 v[2:5], v[164:167], v[216:219], v[2:5]
	v_mfma_f32_16x16x32_bf16 v[50:53], v[160:163], v[188:191], v[50:53]
	v_mfma_f32_16x16x32_bf16 v[42:45], v[180:183], v[188:191], v[42:45]
	v_mfma_f32_16x16x32_bf16 v[34:37], v[160:163], v[204:207], v[34:37]
	v_mfma_f32_16x16x32_bf16 v[26:29], v[180:183], v[204:207], v[26:29]
	v_mfma_f32_16x16x32_bf16 v[18:21], v[160:163], v[212:215], v[18:21]
	v_mfma_f32_16x16x32_bf16 v[10:13], v[180:183], v[212:215], v[10:13]
	v_mfma_f32_16x16x32_bf16 v[6:9], v[160:163], v[220:223], v[6:9]
	v_mfma_f32_16x16x32_bf16 v[2:5], v[180:183], v[220:223], v[2:5]
	s_barrier
	s_mov_b32 s100, 0
	s_add_i32 s93, s93, 2
	s_add_u32 s0, s0, 0x100
	s_addc_u32 s1, s1, 0
	s_add_u32 s91, s91, 0x100
	s_addc_u32 s92, s92, 0
	s_cmp_gt_u32 s93, 13
	s_cbranch_scc0 .LBB0_322
	s_setprio 0
	s_mov_b32 s100, 1
	s_and_b64 vcc, exec, s[14:15]
	s_cbranch_vccz .LBB0_325
	s_barrier

.LBB0_863:
	s_ashr_i32 s57, s56, 31
	s_lshl_b64 s[0:1], s[56:57], 19
	v_readlane_b32 s4, v254, 23
	s_add_u32 s0, s4, s0
	v_readlane_b32 s4, v254, 24
	s_addc_u32 s1, s4, s1
	s_and_b64 s[4:5], s[40:41], exec
	s_cselect_b32 s57, s1, s69
	s_cselect_b32 s95, s0, s68
	s_ashr_i32 s31, s30, 31
	s_lshl_b64 s[4:5], s[30:31], 19
	s_add_u32 s20, s27, s4
	s_addc_u32 s21, s77, s5
	s_and_b64 s[4:5], s[40:41], exec
	s_cselect_b32 s31, s21, s71
	s_cselect_b32 vcc_lo, s20, s70
	s_add_u32 s68, s68, 0x40080
	s_addc_u32 s69, s69, 0
	s_add_u32 vcc_hi, s70, 0x100
	v_mov_b32_e32 v2, 0
	s_addc_u32 s96, s71, 0
	s_mov_b32 s97, -2
	v_mov_b32_e32 v3, v2
	v_mov_b32_e32 v4, v2
	v_mov_b32_e32 v5, v2
	v_mov_b32_e32 v6, v2
	v_mov_b32_e32 v7, v2
	v_mov_b32_e32 v8, v2
	v_mov_b32_e32 v9, v2
	v_mov_b32_e32 v18, v2
	v_mov_b32_e32 v19, v2
	v_mov_b32_e32 v20, v2
	v_mov_b32_e32 v21, v2
	v_mov_b32_e32 v22, v2
	v_mov_b32_e32 v23, v2
	v_mov_b32_e32 v24, v2
	v_mov_b32_e32 v25, v2
	v_mov_b32_e32 v34, v2
	v_mov_b32_e32 v35, v2
	v_mov_b32_e32 v36, v2
	v_mov_b32_e32 v37, v2
	v_mov_b32_e32 v38, v2
	v_mov_b32_e32 v39, v2
	v_mov_b32_e32 v40, v2
	v_mov_b32_e32 v41, v2
	v_mov_b32_e32 v50, v2
	v_mov_b32_e32 v51, v2
	v_mov_b32_e32 v52, v2
	v_mov_b32_e32 v53, v2
	v_mov_b32_e32 v54, v2
	v_mov_b32_e32 v55, v2
	v_mov_b32_e32 v56, v2
	v_mov_b32_e32 v57, v2
	v_mov_b32_e32 v10, v2
	v_mov_b32_e32 v11, v2
	v_mov_b32_e32 v12, v2
	v_mov_b32_e32 v13, v2
	v_mov_b32_e32 v14, v2
	s_waitcnt lgkmcnt(0)
	v_mov_b32_e32 v15, v2
	v_mov_b32_e32 v16, v2
	v_mov_b32_e32 v17, v2
	v_mov_b32_e32 v26, v2
	v_mov_b32_e32 v27, v2
	v_mov_b32_e32 v28, v2
	v_mov_b32_e32 v29, v2
	v_mov_b32_e32 v30, v2
	v_mov_b32_e32 v31, v2
	v_mov_b32_e32 v32, v2
	v_mov_b32_e32 v33, v2
	v_mov_b32_e32 v42, v2
	v_mov_b32_e32 v43, v2
	v_mov_b32_e32 v44, v2
	v_mov_b32_e32 v45, v2
	v_mov_b32_e32 v46, v2
	v_mov_b32_e32 v47, v2
	v_mov_b32_e32 v48, v2
	v_mov_b32_e32 v49, v2
	v_mov_b32_e32 v58, v2
	v_mov_b32_e32 v59, v2
	v_mov_b32_e32 v60, v2
	v_mov_b32_e32 v61, v2
	v_mov_b32_e32 v62, v2
	v_mov_b32_e32 v63, v2
	v_mov_b32_e32 v64, v2
	v_mov_b32_e32 v65, v2
	v_mov_b32_e32 v66, v2
	v_mov_b32_e32 v67, v2
	v_mov_b32_e32 v68, v2
	v_mov_b32_e32 v69, v2
	v_mov_b32_e32 v70, v2
	v_mov_b32_e32 v71, v2
	v_mov_b32_e32 v72, v2
	v_mov_b32_e32 v73, v2
	v_mov_b32_e32 v82, v2
	v_mov_b32_e32 v83, v2
	v_mov_b32_e32 v84, v2
	v_mov_b32_e32 v85, v2
	v_mov_b32_e32 v86, v2
	v_mov_b32_e32 v87, v2
	v_mov_b32_e32 v88, v2
	v_mov_b32_e32 v89, v2
	v_mov_b32_e32 v132, v2
	v_mov_b32_e32 v133, v2
	v_mov_b32_e32 v134, v2
	v_mov_b32_e32 v135, v2
	v_mov_b32_e32 v136, v2
	v_mov_b32_e32 v137, v2
	v_mov_b32_e32 v138, v2
	v_mov_b32_e32 v139, v2
	v_mov_b32_e32 v148, v2
	v_mov_b32_e32 v149, v2
	v_mov_b32_e32 v150, v2
	v_mov_b32_e32 v151, v2
	v_mov_b32_e32 v152, v2
	v_mov_b32_e32 v153, v2
	v_mov_b32_e32 v154, v2
	v_mov_b32_e32 v155, v2
	v_mov_b32_e32 v74, v2
	v_mov_b32_e32 v75, v2
	v_mov_b32_e32 v76, v2
	v_mov_b32_e32 v77, v2
	v_mov_b32_e32 v78, v2
	v_mov_b32_e32 v79, v2
	v_mov_b32_e32 v80, v2
	v_mov_b32_e32 v81, v2
	v_mov_b32_e32 v116, v2
	v_mov_b32_e32 v117, v2
	v_mov_b32_e32 v118, v2
	v_mov_b32_e32 v119, v2
	v_mov_b32_e32 v124, v2
	v_mov_b32_e32 v125, v2
	v_mov_b32_e32 v126, v2
	v_mov_b32_e32 v127, v2
	v_mov_b32_e32 v140, v2
	v_mov_b32_e32 v141, v2
	v_mov_b32_e32 v142, v2
	v_mov_b32_e32 v143, v2
	v_mov_b32_e32 v144, v2
	v_mov_b32_e32 v145, v2
	v_mov_b32_e32 v146, v2
	v_mov_b32_e32 v147, v2
	v_mov_b32_e32 v156, v2
	v_mov_b32_e32 v157, v2
	v_mov_b32_e32 v158, v2
	v_mov_b32_e32 v159, v2
	v_mov_b32_e32 v160, v2
	v_mov_b32_e32 v161, v2
	v_mov_b32_e32 v162, v2
	v_mov_b32_e32 v163, v2
	s_bitcmp1_b32 s91, 12
	s_cbranch_scc0 .Lmy_sp_g2a
	s_setprio 1
.Lmy_sp_g2a:
.LBB0_864:
	s_add_u32 s4, s68, 0xfffc0080
	s_addc_u32 s5, s69, -1
	s_add_i32 s45, 0, 0x10000
	s_cmp_eq_u32 s97, 12
	s_cselect_b32 s75, s57, s5
	s_cselect_b32 s74, s95, s4
	s_cselect_b32 s71, s31, s96
	s_cselect_b32 s70, vcc_lo, vcc_hi
	s_add_i32 s6, 0, 0x14000
	v_add_u32_e32 v104, s45, v239
	v_add_u32_e32 v128, s6, v239
	ds_read_b128 v[90:93], v104
	ds_read_b128 v[94:97], v104 offset:1024
	ds_read_b128 v[100:103], v104 offset:2048
	ds_read_b128 v[104:107], v104 offset:3072
	ds_read_b128 v[108:111], v128
	ds_read_b128 v[112:115], v128 offset:1024
	ds_read_b128 v[120:123], v128 offset:2048
	ds_read_b128 v[128:131], v128 offset:3072
	s_add_i32 s44, s91, 0
	v_lshl_add_u64 v[200:201], s[68:69], 0, v[98:99]
	s_add_i32 m0, s44, 0xc000
	ds_read_b128 v[164:167], v241
	ds_read_b128 v[168:171], v241 offset:1024
	ds_read_b128 v[172:175], v241 offset:2048
	ds_read_b128 v[176:179], v241 offset:3072
	ds_read_b128 v[180:183], v241 offset:4096
	ds_read_b128 v[184:187], v241 offset:5120
	ds_read_b128 v[188:191], v241 offset:6144
	ds_read_b128 v[192:195], v241 offset:7168
	global_load_lds_dwordx4 v[200:201], off
	v_lshl_add_u64 v[200:201], s[68:69], 0, v[206:207]
	s_add_i32 m0, s44, 0xe000
	s_nop 0
	global_load_lds_dwordx4 v[200:201], off
	s_cmp_eq_u32 s100, 1
	s_cbranch_scc1 .Lmy_sk3
	s_waitcnt vmcnt(8)
.Lmy_sk3:
	s_waitcnt lgkmcnt(0)
	s_barrier
	v_mfma_f32_16x16x32_bf16 v[160:163], v[90:93], v[164:167], v[160:163]
	v_mfma_f32_16x16x32_bf16 v[156:159], v[100:103], v[164:167], v[156:159]
	v_mfma_f32_16x16x32_bf16 v[144:147], v[90:93], v[172:175], v[144:147]
	v_mfma_f32_16x16x32_bf16 v[140:143], v[100:103], v[172:175], v[140:143]
	v_mfma_f32_16x16x32_bf16 v[124:127], v[90:93], v[180:183], v[124:127]
	v_mfma_f32_16x16x32_bf16 v[116:119], v[100:103], v[180:183], v[116:119]
	v_mfma_f32_16x16x32_bf16 v[78:81], v[90:93], v[188:191], v[78:81]
	v_mfma_f32_16x16x32_bf16 v[74:77], v[100:103], v[188:191], v[74:77]
	v_mfma_f32_16x16x32_bf16 v[160:163], v[94:97], v[168:171], v[160:163]
	v_mfma_f32_16x16x32_bf16 v[156:159], v[104:107], v[168:171], v[156:159]
	v_mfma_f32_16x16x32_bf16 v[144:147], v[94:97], v[176:179], v[144:147]
	v_mfma_f32_16x16x32_bf16 v[140:143], v[104:107], v[176:179], v[140:143]
	v_mfma_f32_16x16x32_bf16 v[124:127], v[94:97], v[184:187], v[124:127]
	v_mfma_f32_16x16x32_bf16 v[116:119], v[104:107], v[184:187], v[116:119]
	v_mfma_f32_16x16x32_bf16 v[78:81], v[94:97], v[192:195], v[78:81]
	v_mfma_f32_16x16x32_bf16 v[74:77], v[104:107], v[192:195], v[74:77]
	v_mfma_f32_16x16x32_bf16 v[152:155], v[108:111], v[164:167], v[152:155]
	v_mfma_f32_16x16x32_bf16 v[148:151], v[120:123], v[164:167], v[148:151]
	v_mfma_f32_16x16x32_bf16 v[136:139], v[108:111], v[172:175], v[136:139]
	v_mfma_f32_16x16x32_bf16 v[132:135], v[120:123], v[172:175], v[132:135]
	v_mfma_f32_16x16x32_bf16 v[86:89], v[108:111], v[180:183], v[86:89]
	v_mfma_f32_16x16x32_bf16 v[82:85], v[120:123], v[180:183], v[82:85]
	v_mfma_f32_16x16x32_bf16 v[70:73], v[108:111], v[188:191], v[70:73]
	v_mfma_f32_16x16x32_bf16 v[66:69], v[120:123], v[188:191], v[66:69]
	v_mfma_f32_16x16x32_bf16 v[152:155], v[112:115], v[168:171], v[152:155]
	v_mfma_f32_16x16x32_bf16 v[148:151], v[128:131], v[168:171], v[148:151]
	v_mfma_f32_16x16x32_bf16 v[136:139], v[112:115], v[176:179], v[136:139]
	v_mfma_f32_16x16x32_bf16 v[132:135], v[128:131], v[176:179], v[132:135]
	v_mfma_f32_16x16x32_bf16 v[86:89], v[112:115], v[184:187], v[86:89]
	v_mfma_f32_16x16x32_bf16 v[82:85], v[128:131], v[184:187], v[82:85]
	v_mfma_f32_16x16x32_bf16 v[70:73], v[112:115], v[192:195], v[70:73]
	v_mfma_f32_16x16x32_bf16 v[66:69], v[128:131], v[192:195], v[66:69]
	s_barrier
	s_add_i32 s4, s45, s91
	v_lshl_add_u64 v[200:201], s[70:71], 0, v[204:205]
	s_mov_b32 m0, s4
	ds_read_b128 v[164:167], v241 offset:16384
	ds_read_b128 v[168:171], v241 offset:17408
	ds_read_b128 v[172:175], v241 offset:18432
	ds_read_b128 v[176:179], v241 offset:19456
	ds_read_b128 v[180:183], v241 offset:20480
	ds_read_b128 v[184:187], v241 offset:21504
	ds_read_b128 v[188:191], v241 offset:22528
	ds_read_b128 v[192:195], v241 offset:23552
	global_load_lds_dwordx4 v[200:201], off
	s_add_i32 m0, s4, 0x2000
	s_add_u32 s4, s70, 0x40000
	v_lshl_add_u64 v[202:203], s[70:71], 0, v[208:209]
	s_addc_u32 s5, s71, 0
	s_add_i32 s6, s6, s91
	global_load_lds_dwordx4 v[202:203], off
	v_lshl_add_u64 v[210:211], s[4:5], 0, v[204:205]
	s_mov_b32 m0, s6
	v_lshl_add_u64 v[212:213], s[74:75], 0, v[206:207]
	global_load_lds_dwordx4 v[210:211], off
	v_lshl_add_u64 v[210:211], s[4:5], 0, v[208:209]
	s_add_i32 m0, s6, 0x2000
	s_nop 0
	global_load_lds_dwordx4 v[210:211], off
	v_lshl_add_u64 v[210:211], s[74:75], 0, v[98:99]
	s_mov_b32 m0, s44
	s_nop 0
	global_load_lds_dwordx4 v[210:211], off
	s_add_i32 m0, s44, 0x2000
	s_nop 0
	global_load_lds_dwordx4 v[212:213], off
	s_cmp_eq_u32 s100, 1
	s_cbranch_scc1 .Lmy_sk4
	s_waitcnt vmcnt(8)
.Lmy_sk4:
	s_waitcnt lgkmcnt(0)
	s_barrier
	v_mfma_f32_16x16x32_bf16 v[62:65], v[90:93], v[164:167], v[62:65]
	v_mfma_f32_16x16x32_bf16 v[58:61], v[100:103], v[164:167], v[58:61]
	v_mfma_f32_16x16x32_bf16 v[46:49], v[90:93], v[172:175], v[46:49]
	v_mfma_f32_16x16x32_bf16 v[42:45], v[100:103], v[172:175], v[42:45]
	v_mfma_f32_16x16x32_bf16 v[30:33], v[90:93], v[180:183], v[30:33]
	v_mfma_f32_16x16x32_bf16 v[26:29], v[100:103], v[180:183], v[26:29]
	v_mfma_f32_16x16x32_bf16 v[14:17], v[90:93], v[188:191], v[14:17]
	v_mfma_f32_16x16x32_bf16 v[10:13], v[100:103], v[188:191], v[10:13]
	v_mfma_f32_16x16x32_bf16 v[62:65], v[94:97], v[168:171], v[62:65]
	v_mfma_f32_16x16x32_bf16 v[58:61], v[104:107], v[168:171], v[58:61]
	v_mfma_f32_16x16x32_bf16 v[46:49], v[94:97], v[176:179], v[46:49]
	v_mfma_f32_16x16x32_bf16 v[42:45], v[104:107], v[176:179], v[42:45]
	v_mfma_f32_16x16x32_bf16 v[30:33], v[94:97], v[184:187], v[30:33]
	v_mfma_f32_16x16x32_bf16 v[26:29], v[104:107], v[184:187], v[26:29]
	v_mfma_f32_16x16x32_bf16 v[14:17], v[94:97], v[192:195], v[14:17]
	v_mfma_f32_16x16x32_bf16 v[10:13], v[104:107], v[192:195], v[10:13]
	v_mfma_f32_16x16x32_bf16 v[54:57], v[108:111], v[164:167], v[54:57]
	v_mfma_f32_16x16x32_bf16 v[50:53], v[120:123], v[164:167], v[50:53]
	v_mfma_f32_16x16x32_bf16 v[38:41], v[108:111], v[172:175], v[38:41]
	v_mfma_f32_16x16x32_bf16 v[34:37], v[120:123], v[172:175], v[34:37]
	v_mfma_f32_16x16x32_bf16 v[22:25], v[108:111], v[180:183], v[22:25]
	v_mfma_f32_16x16x32_bf16 v[18:21], v[120:123], v[180:183], v[18:21]
	v_mfma_f32_16x16x32_bf16 v[6:9], v[108:111], v[188:191], v[6:9]
	v_mfma_f32_16x16x32_bf16 v[2:5], v[120:123], v[188:191], v[2:5]
	v_mfma_f32_16x16x32_bf16 v[54:57], v[112:115], v[168:171], v[54:57]
	v_mfma_f32_16x16x32_bf16 v[50:53], v[128:131], v[168:171], v[50:53]
	v_mfma_f32_16x16x32_bf16 v[38:41], v[112:115], v[176:179], v[38:41]
	v_mfma_f32_16x16x32_bf16 v[34:37], v[128:131], v[176:179], v[34:37]
	v_mfma_f32_16x16x32_bf16 v[22:25], v[112:115], v[184:187], v[22:25]
	v_mfma_f32_16x16x32_bf16 v[18:21], v[128:131], v[184:187], v[18:21]
	v_mfma_f32_16x16x32_bf16 v[6:9], v[112:115], v[192:195], v[6:9]
	v_mfma_f32_16x16x32_bf16 v[2:5], v[128:131], v[192:195], v[2:5]
	s_barrier
	s_add_i32 s6, 0, 0x18000
	s_add_i32 s7, 0, 0x1c000
	v_add_u32_e32 v104, s6, v239
	v_add_u32_e32 v128, s7, v239
	ds_read_b128 v[90:93], v104
	ds_read_b128 v[94:97], v104 offset:1024
	ds_read_b128 v[100:103], v104 offset:2048
	ds_read_b128 v[104:107], v104 offset:3072
	ds_read_b128 v[108:111], v128
	ds_read_b128 v[112:115], v128 offset:1024
	ds_read_b128 v[120:123], v128 offset:2048
	ds_read_b128 v[128:131], v128 offset:3072
	s_add_u32 s4, s74, 0x40000
	s_addc_u32 s5, s75, 0
	v_lshl_add_u64 v[214:215], s[4:5], 0, v[98:99]
	s_add_i32 m0, s44, 0x4000
	ds_read_b128 v[164:167], v241 offset:32768
	ds_read_b128 v[168:171], v241 offset:33792
	ds_read_b128 v[172:175], v241 offset:34816
	ds_read_b128 v[176:179], v241 offset:35840
	ds_read_b128 v[180:183], v241 offset:36864
	ds_read_b128 v[184:187], v241 offset:37888
	ds_read_b128 v[188:191], v241 offset:38912
	ds_read_b128 v[192:195], v241 offset:39936
	global_load_lds_dwordx4 v[214:215], off
	v_lshl_add_u64 v[214:215], s[4:5], 0, v[206:207]
	s_add_i32 m0, s44, 0x6000
	s_nop 0
	global_load_lds_dwordx4 v[214:215], off
	s_waitcnt vmcnt(8)
	s_waitcnt lgkmcnt(0)
	s_barrier
	v_mfma_f32_16x16x32_bf16 v[160:163], v[90:93], v[164:167], v[160:163]
	v_mfma_f32_16x16x32_bf16 v[156:159], v[100:103], v[164:167], v[156:159]
	v_mfma_f32_16x16x32_bf16 v[144:147], v[90:93], v[172:175], v[144:147]
	v_mfma_f32_16x16x32_bf16 v[140:143], v[100:103], v[172:175], v[140:143]
	v_mfma_f32_16x16x32_bf16 v[124:127], v[90:93], v[180:183], v[124:127]
	v_mfma_f32_16x16x32_bf16 v[116:119], v[100:103], v[180:183], v[116:119]
	v_mfma_f32_16x16x32_bf16 v[78:81], v[90:93], v[188:191], v[78:81]
	v_mfma_f32_16x16x32_bf16 v[74:77], v[100:103], v[188:191], v[74:77]
	v_mfma_f32_16x16x32_bf16 v[160:163], v[94:97], v[168:171], v[160:163]
	v_mfma_f32_16x16x32_bf16 v[156:159], v[104:107], v[168:171], v[156:159]
	v_mfma_f32_16x16x32_bf16 v[144:147], v[94:97], v[176:179], v[144:147]
	v_mfma_f32_16x16x32_bf16 v[140:143], v[104:107], v[176:179], v[140:143]
	v_mfma_f32_16x16x32_bf16 v[124:127], v[94:97], v[184:187], v[124:127]
	v_mfma_f32_16x16x32_bf16 v[116:119], v[104:107], v[184:187], v[116:119]
	v_mfma_f32_16x16x32_bf16 v[78:81], v[94:97], v[192:195], v[78:81]
	v_mfma_f32_16x16x32_bf16 v[74:77], v[104:107], v[192:195], v[74:77]
	v_mfma_f32_16x16x32_bf16 v[152:155], v[108:111], v[164:167], v[152:155]
	v_mfma_f32_16x16x32_bf16 v[148:151], v[120:123], v[164:167], v[148:151]
	v_mfma_f32_16x16x32_bf16 v[136:139], v[108:111], v[172:175], v[136:139]
	v_mfma_f32_16x16x32_bf16 v[132:135], v[120:123], v[172:175], v[132:135]
	v_mfma_f32_16x16x32_bf16 v[86:89], v[108:111], v[180:183], v[86:89]
	v_mfma_f32_16x16x32_bf16 v[82:85], v[120:123], v[180:183], v[82:85]
	v_mfma_f32_16x16x32_bf16 v[70:73], v[108:111], v[188:191], v[70:73]
	v_mfma_f32_16x16x32_bf16 v[66:69], v[120:123], v[188:191], v[66:69]
	v_mfma_f32_16x16x32_bf16 v[152:155], v[112:115], v[168:171], v[152:155]
	v_mfma_f32_16x16x32_bf16 v[148:151], v[128:131], v[168:171], v[148:151]
	v_mfma_f32_16x16x32_bf16 v[136:139], v[112:115], v[176:179], v[136:139]
	v_mfma_f32_16x16x32_bf16 v[132:135], v[128:131], v[176:179], v[132:135]
	v_mfma_f32_16x16x32_bf16 v[86:89], v[112:115], v[184:187], v[86:89]
	v_mfma_f32_16x16x32_bf16 v[82:85], v[128:131], v[184:187], v[82:85]
	v_mfma_f32_16x16x32_bf16 v[70:73], v[112:115], v[192:195], v[70:73]
	v_mfma_f32_16x16x32_bf16 v[66:69], v[128:131], v[192:195], v[66:69]
	s_barrier
	s_add_i32 s4, s6, s91
	v_lshl_add_u64 v[200:201], v[200:201], 0, s[42:43]
	s_mov_b32 m0, s4
	ds_read_b128 v[164:167], v241 offset:49152
	ds_read_b128 v[168:171], v241 offset:50176
	ds_read_b128 v[172:175], v241 offset:51200
	ds_read_b128 v[176:179], v241 offset:52224
	ds_read_b128 v[180:183], v241 offset:53248
	ds_read_b128 v[184:187], v241 offset:54272
	ds_read_b128 v[188:191], v241 offset:55296
	ds_read_b128 v[192:195], v241 offset:56320
	global_load_lds_dwordx4 v[200:201], off
	s_add_i32 m0, s4, 0x2000
	s_add_u32 s4, s70, 0x40080
	v_lshl_add_u64 v[200:201], v[202:203], 0, s[42:43]
	s_addc_u32 s5, s71, 0
	s_add_i32 s6, s7, s91
	global_load_lds_dwordx4 v[200:201], off
	v_lshl_add_u64 v[200:201], s[4:5], 0, v[204:205]
	s_mov_b32 m0, s6
	s_nop 0
	global_load_lds_dwordx4 v[200:201], off
	v_lshl_add_u64 v[200:201], s[4:5], 0, v[208:209]
	s_add_i32 m0, s6, 0x2000
	s_nop 0
	global_load_lds_dwordx4 v[200:201], off
	v_lshl_add_u64 v[200:201], v[210:211], 0, s[42:43]
	s_add_i32 m0, s44, 0x8000
	s_nop 0
	global_load_lds_dwordx4 v[200:201], off
	v_lshl_add_u64 v[200:201], v[212:213], 0, s[42:43]
	s_add_i32 m0, s44, 0xa000
	s_nop 0
	global_load_lds_dwordx4 v[200:201], off
	s_waitcnt vmcnt(8)
	s_waitcnt lgkmcnt(0)
	s_barrier
	v_mfma_f32_16x16x32_bf16 v[62:65], v[90:93], v[164:167], v[62:65]
	v_mfma_f32_16x16x32_bf16 v[58:61], v[100:103], v[164:167], v[58:61]
	v_mfma_f32_16x16x32_bf16 v[46:49], v[90:93], v[172:175], v[46:49]
	v_mfma_f32_16x16x32_bf16 v[42:45], v[100:103], v[172:175], v[42:45]
	v_mfma_f32_16x16x32_bf16 v[30:33], v[90:93], v[180:183], v[30:33]
	v_mfma_f32_16x16x32_bf16 v[26:29], v[100:103], v[180:183], v[26:29]
	v_mfma_f32_16x16x32_bf16 v[14:17], v[90:93], v[188:191], v[14:17]
	v_mfma_f32_16x16x32_bf16 v[10:13], v[100:103], v[188:191], v[10:13]
	v_mfma_f32_16x16x32_bf16 v[62:65], v[94:97], v[168:171], v[62:65]
	v_mfma_f32_16x16x32_bf16 v[58:61], v[104:107], v[168:171], v[58:61]
	v_mfma_f32_16x16x32_bf16 v[46:49], v[94:97], v[176:179], v[46:49]
	v_mfma_f32_16x16x32_bf16 v[42:45], v[104:107], v[176:179], v[42:45]
	v_mfma_f32_16x16x32_bf16 v[30:33], v[94:97], v[184:187], v[30:33]
	v_mfma_f32_16x16x32_bf16 v[26:29], v[104:107], v[184:187], v[26:29]
	v_mfma_f32_16x16x32_bf16 v[14:17], v[94:97], v[192:195], v[14:17]
	v_mfma_f32_16x16x32_bf16 v[10:13], v[104:107], v[192:195], v[10:13]
	v_mfma_f32_16x16x32_bf16 v[54:57], v[108:111], v[164:167], v[54:57]
	v_mfma_f32_16x16x32_bf16 v[50:53], v[120:123], v[164:167], v[50:53]
	v_mfma_f32_16x16x32_bf16 v[38:41], v[108:111], v[172:175], v[38:41]
	v_mfma_f32_16x16x32_bf16 v[34:37], v[120:123], v[172:175], v[34:37]
	v_mfma_f32_16x16x32_bf16 v[22:25], v[108:111], v[180:183], v[22:25]
	v_mfma_f32_16x16x32_bf16 v[18:21], v[120:123], v[180:183], v[18:21]
	v_mfma_f32_16x16x32_bf16 v[6:9], v[108:111], v[188:191], v[6:9]
	v_mfma_f32_16x16x32_bf16 v[2:5], v[120:123], v[188:191], v[2:5]
	v_mfma_f32_16x16x32_bf16 v[54:57], v[112:115], v[168:171], v[54:57]
	v_mfma_f32_16x16x32_bf16 v[50:53], v[128:131], v[168:171], v[50:53]
	v_mfma_f32_16x16x32_bf16 v[38:41], v[112:115], v[176:179], v[38:41]
	v_mfma_f32_16x16x32_bf16 v[34:37], v[128:131], v[176:179], v[34:37]
	v_mfma_f32_16x16x32_bf16 v[22:25], v[112:115], v[184:187], v[22:25]
	v_mfma_f32_16x16x32_bf16 v[18:21], v[128:131], v[184:187], v[18:21]
	v_mfma_f32_16x16x32_bf16 v[6:9], v[112:115], v[192:195], v[6:9]
	v_mfma_f32_16x16x32_bf16 v[2:5], v[128:131], v[192:195], v[2:5]
	s_barrier
	s_mov_b32 s100, 0
	s_add_i32 s97, s97, 2
	s_add_u32 s68, s68, 0x100
	s_addc_u32 s69, s69, 0
	s_add_u32 vcc_hi, vcc_hi, 0x100
	s_addc_u32 s96, s96, 0
	s_cmp_gt_u32 s97, 13
	s_cbranch_scc0 .LBB0_864
	s_setprio 0
	s_mov_b32 s100, 1
	s_and_b64 vcc, exec, s[12:13]
	s_cbranch_vccz .LBB0_867
	s_barrier

.LBB0_907:
	s_ashr_i32 s21, s20, 31
	s_lshl_b64 s[30:31], s[20:21], 19
	v_readlane_b32 s2, v254, 23
	s_add_u32 s30, s2, s30
	v_readlane_b32 s2, v254, 24
	s_addc_u32 s31, s2, s31
	s_and_b64 s[40:41], s[38:39], exec
	s_cselect_b32 s21, s31, s57
	s_cselect_b32 s93, s30, s56
	s_ashr_i32 s53, s52, 31
	s_lshl_b64 s[40:41], s[52:53], 19
	s_add_u32 s40, s27, s40
	s_addc_u32 s41, s77, s41
	s_and_b64 s[44:45], s[38:39], exec
	s_cselect_b32 s15, s41, s69
	s_cselect_b32 s94, s40, s68
	s_add_u32 s56, s56, 0x40080
	s_addc_u32 s57, s57, 0
	s_add_u32 s95, s68, 0x100
	v_mov_b32_e32 v2, 0
	s_addc_u32 vcc_lo, s69, 0
	s_mov_b32 s96, -2
	v_mov_b32_e32 v3, v2
	v_mov_b32_e32 v4, v2
	v_mov_b32_e32 v5, v2
	v_mov_b32_e32 v6, v2
	v_mov_b32_e32 v7, v2
	v_mov_b32_e32 v8, v2
	v_mov_b32_e32 v9, v2
	v_mov_b32_e32 v18, v2
	v_mov_b32_e32 v19, v2
	v_mov_b32_e32 v20, v2
	v_mov_b32_e32 v21, v2
	v_mov_b32_e32 v22, v2
	v_mov_b32_e32 v23, v2
	v_mov_b32_e32 v24, v2
	v_mov_b32_e32 v25, v2
	v_mov_b32_e32 v34, v2
	v_mov_b32_e32 v35, v2
	v_mov_b32_e32 v36, v2
	v_mov_b32_e32 v37, v2
	v_mov_b32_e32 v38, v2
	v_mov_b32_e32 v39, v2
	v_mov_b32_e32 v40, v2
	v_mov_b32_e32 v41, v2
	v_mov_b32_e32 v50, v2
	v_mov_b32_e32 v51, v2
	v_mov_b32_e32 v52, v2
	v_mov_b32_e32 v53, v2
	v_mov_b32_e32 v54, v2
	v_mov_b32_e32 v55, v2
	v_mov_b32_e32 v56, v2
	v_mov_b32_e32 v57, v2
	v_mov_b32_e32 v10, v2
	v_mov_b32_e32 v11, v2
	v_mov_b32_e32 v12, v2
	v_mov_b32_e32 v13, v2
	v_mov_b32_e32 v14, v2
	v_mov_b32_e32 v15, v2
	v_mov_b32_e32 v16, v2
	v_mov_b32_e32 v17, v2
	v_mov_b32_e32 v26, v2
	v_mov_b32_e32 v27, v2
	v_mov_b32_e32 v28, v2
	v_mov_b32_e32 v29, v2
	v_mov_b32_e32 v30, v2
	v_mov_b32_e32 v31, v2
	v_mov_b32_e32 v32, v2
	v_mov_b32_e32 v33, v2
	v_mov_b32_e32 v42, v2
	v_mov_b32_e32 v43, v2
	v_mov_b32_e32 v44, v2
	v_mov_b32_e32 v45, v2
	v_mov_b32_e32 v46, v2
	v_mov_b32_e32 v47, v2
	v_mov_b32_e32 v48, v2
	v_mov_b32_e32 v49, v2
	v_mov_b32_e32 v58, v2
	v_mov_b32_e32 v59, v2
	v_mov_b32_e32 v60, v2
	v_mov_b32_e32 v61, v2
	v_mov_b32_e32 v62, v2
	v_mov_b32_e32 v63, v2
	v_mov_b32_e32 v64, v2
	v_mov_b32_e32 v65, v2
	v_mov_b32_e32 v66, v2
	v_mov_b32_e32 v67, v2
	v_mov_b32_e32 v68, v2
	v_mov_b32_e32 v69, v2
	v_mov_b32_e32 v70, v2
	v_mov_b32_e32 v71, v2
	v_mov_b32_e32 v72, v2
	v_mov_b32_e32 v73, v2
	v_mov_b32_e32 v82, v2
	v_mov_b32_e32 v83, v2
	v_mov_b32_e32 v84, v2
	v_mov_b32_e32 v85, v2
	v_mov_b32_e32 v94, v2
	v_mov_b32_e32 v95, v2
	v_mov_b32_e32 v96, v2
	v_mov_b32_e32 v97, v2
	v_mov_b32_e32 v132, v2
	v_mov_b32_e32 v133, v2
	v_mov_b32_e32 v134, v2
	v_mov_b32_e32 v135, v2
	v_mov_b32_e32 v136, v2
	v_mov_b32_e32 v137, v2
	v_mov_b32_e32 v138, v2
	v_mov_b32_e32 v139, v2
	v_mov_b32_e32 v148, v2
	v_mov_b32_e32 v149, v2
	v_mov_b32_e32 v150, v2
	v_mov_b32_e32 v151, v2
	v_mov_b32_e32 v152, v2
	v_mov_b32_e32 v153, v2
	v_mov_b32_e32 v154, v2
	v_mov_b32_e32 v155, v2
	v_mov_b32_e32 v74, v2
	v_mov_b32_e32 v75, v2
	v_mov_b32_e32 v76, v2
	v_mov_b32_e32 v77, v2
	v_mov_b32_e32 v78, v2
	v_mov_b32_e32 v79, v2
	v_mov_b32_e32 v80, v2
	v_mov_b32_e32 v81, v2
	v_mov_b32_e32 v120, v2
	v_mov_b32_e32 v121, v2
	v_mov_b32_e32 v122, v2
	v_mov_b32_e32 v123, v2
	v_mov_b32_e32 v128, v2
	v_mov_b32_e32 v129, v2
	v_mov_b32_e32 v130, v2
	v_mov_b32_e32 v131, v2
	v_mov_b32_e32 v140, v2
	v_mov_b32_e32 v141, v2
	v_mov_b32_e32 v142, v2
	v_mov_b32_e32 v143, v2
	v_mov_b32_e32 v144, v2
	v_mov_b32_e32 v145, v2
	v_mov_b32_e32 v146, v2
	v_mov_b32_e32 v147, v2
	v_mov_b32_e32 v156, v2
	v_mov_b32_e32 v157, v2
	v_mov_b32_e32 v158, v2
	v_mov_b32_e32 v159, v2
	v_mov_b32_e32 v160, v2
	v_mov_b32_e32 v161, v2
	v_mov_b32_e32 v162, v2
	v_mov_b32_e32 v163, v2
	s_bitcmp1_b32 s74, 12
	s_cbranch_scc0 .Lmy_sp_g2b
	s_setprio 1
.Lmy_sp_g2b:
.LBB0_908:
	s_add_u32 s4, s56, 0xfffc0080
	s_addc_u32 s5, s57, -1
	s_add_i32 s45, 0, 0x10000
	s_cmp_eq_u32 s96, 12
	s_cselect_b32 s71, s21, s5
	s_cselect_b32 s70, s93, s4
	s_cselect_b32 s69, s15, vcc_lo
	s_cselect_b32 s68, s94, s95
	s_add_i32 s97, 0, 0x14000
	v_add_u32_e32 v104, s45, v223
	v_add_u32_e32 v124, s97, v223
	ds_read_b128 v[86:89], v104
	ds_read_b128 v[90:93], v104 offset:1024
	ds_read_b128 v[100:103], v104 offset:2048
	ds_read_b128 v[104:107], v104 offset:3072
	ds_read_b128 v[108:111], v124
	ds_read_b128 v[112:115], v124 offset:1024
	ds_read_b128 v[116:119], v124 offset:2048
	ds_read_b128 v[124:127], v124 offset:3072
	s_add_i32 s44, s74, 0
	v_lshl_add_u64 v[200:201], s[56:57], 0, v[98:99]
	s_add_i32 m0, s44, 0xc000
	ds_read_b128 v[164:167], v225
	ds_read_b128 v[168:171], v225 offset:1024
	ds_read_b128 v[172:175], v225 offset:2048
	ds_read_b128 v[176:179], v225 offset:3072
	ds_read_b128 v[180:183], v225 offset:4096
	ds_read_b128 v[184:187], v225 offset:5120
	ds_read_b128 v[188:191], v225 offset:6144
	ds_read_b128 v[192:195], v225 offset:7168
	global_load_lds_dwordx4 v[200:201], off
	v_lshl_add_u64 v[200:201], s[56:57], 0, v[206:207]
	s_add_i32 m0, s44, 0xe000
	s_nop 0
	global_load_lds_dwordx4 v[200:201], off
	s_cmp_eq_u32 s100, 1
	s_cbranch_scc1 .Lmy_sk5
	s_waitcnt vmcnt(8)
.Lmy_sk5:
	s_waitcnt lgkmcnt(0)
	s_barrier
	v_mfma_f32_16x16x32_bf16 v[160:163], v[86:89], v[164:167], v[160:163]
	v_mfma_f32_16x16x32_bf16 v[156:159], v[100:103], v[164:167], v[156:159]
	v_mfma_f32_16x16x32_bf16 v[144:147], v[86:89], v[172:175], v[144:147]
	v_mfma_f32_16x16x32_bf16 v[140:143], v[100:103], v[172:175], v[140:143]
	v_mfma_f32_16x16x32_bf16 v[128:131], v[86:89], v[180:183], v[128:131]
	v_mfma_f32_16x16x32_bf16 v[120:123], v[100:103], v[180:183], v[120:123]
	v_mfma_f32_16x16x32_bf16 v[78:81], v[86:89], v[188:191], v[78:81]
	v_mfma_f32_16x16x32_bf16 v[74:77], v[100:103], v[188:191], v[74:77]
	v_mfma_f32_16x16x32_bf16 v[160:163], v[90:93], v[168:171], v[160:163]
	v_mfma_f32_16x16x32_bf16 v[156:159], v[104:107], v[168:171], v[156:159]
	v_mfma_f32_16x16x32_bf16 v[144:147], v[90:93], v[176:179], v[144:147]
	v_mfma_f32_16x16x32_bf16 v[140:143], v[104:107], v[176:179], v[140:143]
	v_mfma_f32_16x16x32_bf16 v[128:131], v[90:93], v[184:187], v[128:131]
	v_mfma_f32_16x16x32_bf16 v[120:123], v[104:107], v[184:187], v[120:123]
	v_mfma_f32_16x16x32_bf16 v[78:81], v[90:93], v[192:195], v[78:81]
	v_mfma_f32_16x16x32_bf16 v[74:77], v[104:107], v[192:195], v[74:77]
	v_mfma_f32_16x16x32_bf16 v[152:155], v[108:111], v[164:167], v[152:155]
	v_mfma_f32_16x16x32_bf16 v[148:151], v[116:119], v[164:167], v[148:151]
	v_mfma_f32_16x16x32_bf16 v[136:139], v[108:111], v[172:175], v[136:139]
	v_mfma_f32_16x16x32_bf16 v[132:135], v[116:119], v[172:175], v[132:135]
	v_mfma_f32_16x16x32_bf16 v[94:97], v[108:111], v[180:183], v[94:97]
	v_mfma_f32_16x16x32_bf16 v[82:85], v[116:119], v[180:183], v[82:85]
	v_mfma_f32_16x16x32_bf16 v[70:73], v[108:111], v[188:191], v[70:73]
	v_mfma_f32_16x16x32_bf16 v[66:69], v[116:119], v[188:191], v[66:69]
	v_mfma_f32_16x16x32_bf16 v[152:155], v[112:115], v[168:171], v[152:155]
	v_mfma_f32_16x16x32_bf16 v[148:151], v[124:127], v[168:171], v[148:151]
	v_mfma_f32_16x16x32_bf16 v[136:139], v[112:115], v[176:179], v[136:139]
	v_mfma_f32_16x16x32_bf16 v[132:135], v[124:127], v[176:179], v[132:135]
	v_mfma_f32_16x16x32_bf16 v[94:97], v[112:115], v[184:187], v[94:97]
	v_mfma_f32_16x16x32_bf16 v[82:85], v[124:127], v[184:187], v[82:85]
	v_mfma_f32_16x16x32_bf16 v[70:73], v[112:115], v[192:195], v[70:73]
	v_mfma_f32_16x16x32_bf16 v[66:69], v[124:127], v[192:195], v[66:69]
	s_barrier
	s_add_i32 s4, s45, s74
	v_lshl_add_u64 v[200:201], s[68:69], 0, v[204:205]
	s_mov_b32 m0, s4
	ds_read_b128 v[164:167], v225 offset:16384
	ds_read_b128 v[168:171], v225 offset:17408
	ds_read_b128 v[172:175], v225 offset:18432
	ds_read_b128 v[176:179], v225 offset:19456
	ds_read_b128 v[180:183], v225 offset:20480
	ds_read_b128 v[184:187], v225 offset:21504
	ds_read_b128 v[188:191], v225 offset:22528
	ds_read_b128 v[192:195], v225 offset:23552
	global_load_lds_dwordx4 v[200:201], off
	s_add_i32 m0, s4, 0x2000
	s_add_u32 s4, s68, 0x40000
	v_lshl_add_u64 v[202:203], s[68:69], 0, v[208:209]
	s_addc_u32 s5, s69, 0
	s_add_i32 s45, s97, s74
	global_load_lds_dwordx4 v[202:203], off
	v_lshl_add_u64 v[210:211], s[4:5], 0, v[204:205]
	s_mov_b32 m0, s45
	v_lshl_add_u64 v[212:213], s[70:71], 0, v[206:207]
	global_load_lds_dwordx4 v[210:211], off
	v_lshl_add_u64 v[210:211], s[4:5], 0, v[208:209]
	s_add_i32 m0, s45, 0x2000
	s_nop 0
	global_load_lds_dwordx4 v[210:211], off
	v_lshl_add_u64 v[210:211], s[70:71], 0, v[98:99]
	s_mov_b32 m0, s44
	s_nop 0
	global_load_lds_dwordx4 v[210:211], off
	s_add_i32 m0, s44, 0x2000
	s_nop 0
	global_load_lds_dwordx4 v[212:213], off
	s_cmp_eq_u32 s100, 1
	s_cbranch_scc1 .Lmy_sk6
	s_waitcnt vmcnt(8)
.Lmy_sk6:
	s_waitcnt lgkmcnt(0)
	s_barrier
	v_mfma_f32_16x16x32_bf16 v[62:65], v[86:89], v[164:167], v[62:65]
	v_mfma_f32_16x16x32_bf16 v[58:61], v[100:103], v[164:167], v[58:61]
	v_mfma_f32_16x16x32_bf16 v[46:49], v[86:89], v[172:175], v[46:49]
	v_mfma_f32_16x16x32_bf16 v[42:45], v[100:103], v[172:175], v[42:45]
	v_mfma_f32_16x16x32_bf16 v[30:33], v[86:89], v[180:183], v[30:33]
	v_mfma_f32_16x16x32_bf16 v[26:29], v[100:103], v[180:183], v[26:29]
	v_mfma_f32_16x16x32_bf16 v[14:17], v[86:89], v[188:191], v[14:17]
	v_mfma_f32_16x16x32_bf16 v[10:13], v[100:103], v[188:191], v[10:13]
	v_mfma_f32_16x16x32_bf16 v[62:65], v[90:93], v[168:171], v[62:65]
	v_mfma_f32_16x16x32_bf16 v[58:61], v[104:107], v[168:171], v[58:61]
	v_mfma_f32_16x16x32_bf16 v[46:49], v[90:93], v[176:179], v[46:49]
	v_mfma_f32_16x16x32_bf16 v[42:45], v[104:107], v[176:179], v[42:45]
	v_mfma_f32_16x16x32_bf16 v[30:33], v[90:93], v[184:187], v[30:33]
	v_mfma_f32_16x16x32_bf16 v[26:29], v[104:107], v[184:187], v[26:29]
	v_mfma_f32_16x16x32_bf16 v[14:17], v[90:93], v[192:195], v[14:17]
	v_mfma_f32_16x16x32_bf16 v[10:13], v[104:107], v[192:195], v[10:13]
	v_mfma_f32_16x16x32_bf16 v[54:57], v[108:111], v[164:167], v[54:57]
	v_mfma_f32_16x16x32_bf16 v[50:53], v[116:119], v[164:167], v[50:53]
	v_mfma_f32_16x16x32_bf16 v[38:41], v[108:111], v[172:175], v[38:41]
	v_mfma_f32_16x16x32_bf16 v[34:37], v[116:119], v[172:175], v[34:37]
	v_mfma_f32_16x16x32_bf16 v[22:25], v[108:111], v[180:183], v[22:25]
	v_mfma_f32_16x16x32_bf16 v[18:21], v[116:119], v[180:183], v[18:21]
	v_mfma_f32_16x16x32_bf16 v[6:9], v[108:111], v[188:191], v[6:9]
	v_mfma_f32_16x16x32_bf16 v[2:5], v[116:119], v[188:191], v[2:5]
	v_mfma_f32_16x16x32_bf16 v[54:57], v[112:115], v[168:171], v[54:57]
	v_mfma_f32_16x16x32_bf16 v[50:53], v[124:127], v[168:171], v[50:53]
	v_mfma_f32_16x16x32_bf16 v[38:41], v[112:115], v[176:179], v[38:41]
	v_mfma_f32_16x16x32_bf16 v[34:37], v[124:127], v[176:179], v[34:37]
	v_mfma_f32_16x16x32_bf16 v[22:25], v[112:115], v[184:187], v[22:25]
	v_mfma_f32_16x16x32_bf16 v[18:21], v[124:127], v[184:187], v[18:21]
	v_mfma_f32_16x16x32_bf16 v[6:9], v[112:115], v[192:195], v[6:9]
	v_mfma_f32_16x16x32_bf16 v[2:5], v[124:127], v[192:195], v[2:5]
	s_barrier
	s_add_i32 s45, 0, 0x18000
	s_add_i32 s97, 0, 0x1c000
	v_add_u32_e32 v104, s45, v223
	v_add_u32_e32 v124, s97, v223
	ds_read_b128 v[86:89], v104
	ds_read_b128 v[90:93], v104 offset:1024
	ds_read_b128 v[100:103], v104 offset:2048
	ds_read_b128 v[104:107], v104 offset:3072
	ds_read_b128 v[108:111], v124
	ds_read_b128 v[112:115], v124 offset:1024
	ds_read_b128 v[116:119], v124 offset:2048
	ds_read_b128 v[124:127], v124 offset:3072
	s_add_u32 s4, s70, 0x40000
	s_addc_u32 s5, s71, 0
	v_lshl_add_u64 v[214:215], s[4:5], 0, v[98:99]
	s_add_i32 m0, s44, 0x4000
	ds_read_b128 v[164:167], v225 offset:32768
	ds_read_b128 v[168:171], v225 offset:33792
	ds_read_b128 v[172:175], v225 offset:34816
	ds_read_b128 v[176:179], v225 offset:35840
	ds_read_b128 v[180:183], v225 offset:36864
	ds_read_b128 v[184:187], v225 offset:37888
	ds_read_b128 v[188:191], v225 offset:38912
	ds_read_b128 v[192:195], v225 offset:39936
	global_load_lds_dwordx4 v[214:215], off
	v_lshl_add_u64 v[214:215], s[4:5], 0, v[206:207]
	s_add_i32 m0, s44, 0x6000
	s_nop 0
	global_load_lds_dwordx4 v[214:215], off
	s_waitcnt vmcnt(8)
	s_waitcnt lgkmcnt(0)
	s_barrier
	v_mfma_f32_16x16x32_bf16 v[160:163], v[86:89], v[164:167], v[160:163]
	v_mfma_f32_16x16x32_bf16 v[156:159], v[100:103], v[164:167], v[156:159]
	v_mfma_f32_16x16x32_bf16 v[144:147], v[86:89], v[172:175], v[144:147]
	v_mfma_f32_16x16x32_bf16 v[140:143], v[100:103], v[172:175], v[140:143]
	v_mfma_f32_16x16x32_bf16 v[128:131], v[86:89], v[180:183], v[128:131]
	v_mfma_f32_16x16x32_bf16 v[120:123], v[100:103], v[180:183], v[120:123]
	v_mfma_f32_16x16x32_bf16 v[78:81], v[86:89], v[188:191], v[78:81]
	v_mfma_f32_16x16x32_bf16 v[74:77], v[100:103], v[188:191], v[74:77]
	v_mfma_f32_16x16x32_bf16 v[160:163], v[90:93], v[168:171], v[160:163]
	v_mfma_f32_16x16x32_bf16 v[156:159], v[104:107], v[168:171], v[156:159]
	v_mfma_f32_16x16x32_bf16 v[144:147], v[90:93], v[176:179], v[144:147]
	v_mfma_f32_16x16x32_bf16 v[140:143], v[104:107], v[176:179], v[140:143]
	v_mfma_f32_16x16x32_bf16 v[128:131], v[90:93], v[184:187], v[128:131]
	v_mfma_f32_16x16x32_bf16 v[120:123], v[104:107], v[184:187], v[120:123]
	v_mfma_f32_16x16x32_bf16 v[78:81], v[90:93], v[192:195], v[78:81]
	v_mfma_f32_16x16x32_bf16 v[74:77], v[104:107], v[192:195], v[74:77]
	v_mfma_f32_16x16x32_bf16 v[152:155], v[108:111], v[164:167], v[152:155]
	v_mfma_f32_16x16x32_bf16 v[148:151], v[116:119], v[164:167], v[148:151]
	v_mfma_f32_16x16x32_bf16 v[136:139], v[108:111], v[172:175], v[136:139]
	v_mfma_f32_16x16x32_bf16 v[132:135], v[116:119], v[172:175], v[132:135]
	v_mfma_f32_16x16x32_bf16 v[94:97], v[108:111], v[180:183], v[94:97]
	v_mfma_f32_16x16x32_bf16 v[82:85], v[116:119], v[180:183], v[82:85]
	v_mfma_f32_16x16x32_bf16 v[70:73], v[108:111], v[188:191], v[70:73]
	v_mfma_f32_16x16x32_bf16 v[66:69], v[116:119], v[188:191], v[66:69]
	v_mfma_f32_16x16x32_bf16 v[152:155], v[112:115], v[168:171], v[152:155]
	v_mfma_f32_16x16x32_bf16 v[148:151], v[124:127], v[168:171], v[148:151]
	v_mfma_f32_16x16x32_bf16 v[136:139], v[112:115], v[176:179], v[136:139]
	v_mfma_f32_16x16x32_bf16 v[132:135], v[124:127], v[176:179], v[132:135]
	v_mfma_f32_16x16x32_bf16 v[94:97], v[112:115], v[184:187], v[94:97]
	v_mfma_f32_16x16x32_bf16 v[82:85], v[124:127], v[184:187], v[82:85]
	v_mfma_f32_16x16x32_bf16 v[70:73], v[112:115], v[192:195], v[70:73]
	v_mfma_f32_16x16x32_bf16 v[66:69], v[124:127], v[192:195], v[66:69]
	s_barrier
	s_add_i32 s4, s45, s74
	v_lshl_add_u64 v[200:201], v[200:201], 0, s[42:43]
	s_mov_b32 m0, s4
	ds_read_b128 v[164:167], v225 offset:49152
	ds_read_b128 v[168:171], v225 offset:50176
	ds_read_b128 v[172:175], v225 offset:51200
	ds_read_b128 v[176:179], v225 offset:52224
	ds_read_b128 v[180:183], v225 offset:53248
	ds_read_b128 v[184:187], v225 offset:54272
	ds_read_b128 v[188:191], v225 offset:55296
	ds_read_b128 v[192:195], v225 offset:56320
	global_load_lds_dwordx4 v[200:201], off
	s_add_i32 m0, s4, 0x2000
	s_add_u32 s4, s68, 0x40080
	v_lshl_add_u64 v[200:201], v[202:203], 0, s[42:43]
	s_addc_u32 s5, s69, 0
	s_add_i32 s45, s97, s74
	global_load_lds_dwordx4 v[200:201], off
	v_lshl_add_u64 v[200:201], s[4:5], 0, v[204:205]
	s_mov_b32 m0, s45
	s_nop 0
	global_load_lds_dwordx4 v[200:201], off
	v_lshl_add_u64 v[200:201], s[4:5], 0, v[208:209]
	s_add_i32 m0, s45, 0x2000
	s_nop 0
	global_load_lds_dwordx4 v[200:201], off
	v_lshl_add_u64 v[200:201], v[210:211], 0, s[42:43]
	s_add_i32 m0, s44, 0x8000
	s_nop 0
	global_load_lds_dwordx4 v[200:201], off
	v_lshl_add_u64 v[200:201], v[212:213], 0, s[42:43]
	s_add_i32 m0, s44, 0xa000
	s_nop 0
	global_load_lds_dwordx4 v[200:201], off
	s_waitcnt vmcnt(8)
	s_waitcnt lgkmcnt(0)
	s_barrier
	v_mfma_f32_16x16x32_bf16 v[62:65], v[86:89], v[164:167], v[62:65]
	v_mfma_f32_16x16x32_bf16 v[58:61], v[100:103], v[164:167], v[58:61]
	v_mfma_f32_16x16x32_bf16 v[46:49], v[86:89], v[172:175], v[46:49]
	v_mfma_f32_16x16x32_bf16 v[42:45], v[100:103], v[172:175], v[42:45]
	v_mfma_f32_16x16x32_bf16 v[30:33], v[86:89], v[180:183], v[30:33]
	v_mfma_f32_16x16x32_bf16 v[26:29], v[100:103], v[180:183], v[26:29]
	v_mfma_f32_16x16x32_bf16 v[14:17], v[86:89], v[188:191], v[14:17]
	v_mfma_f32_16x16x32_bf16 v[10:13], v[100:103], v[188:191], v[10:13]
	v_mfma_f32_16x16x32_bf16 v[62:65], v[90:93], v[168:171], v[62:65]
	v_mfma_f32_16x16x32_bf16 v[58:61], v[104:107], v[168:171], v[58:61]
	v_mfma_f32_16x16x32_bf16 v[46:49], v[90:93], v[176:179], v[46:49]
	v_mfma_f32_16x16x32_bf16 v[42:45], v[104:107], v[176:179], v[42:45]
	v_mfma_f32_16x16x32_bf16 v[30:33], v[90:93], v[184:187], v[30:33]
	v_mfma_f32_16x16x32_bf16 v[26:29], v[104:107], v[184:187], v[26:29]
	v_mfma_f32_16x16x32_bf16 v[14:17], v[90:93], v[192:195], v[14:17]
	v_mfma_f32_16x16x32_bf16 v[10:13], v[104:107], v[192:195], v[10:13]
	v_mfma_f32_16x16x32_bf16 v[54:57], v[108:111], v[164:167], v[54:57]
	v_mfma_f32_16x16x32_bf16 v[50:53], v[116:119], v[164:167], v[50:53]
	v_mfma_f32_16x16x32_bf16 v[38:41], v[108:111], v[172:175], v[38:41]
	v_mfma_f32_16x16x32_bf16 v[34:37], v[116:119], v[172:175], v[34:37]
	v_mfma_f32_16x16x32_bf16 v[22:25], v[108:111], v[180:183], v[22:25]
	v_mfma_f32_16x16x32_bf16 v[18:21], v[116:119], v[180:183], v[18:21]
	v_mfma_f32_16x16x32_bf16 v[6:9], v[108:111], v[188:191], v[6:9]
	v_mfma_f32_16x16x32_bf16 v[2:5], v[116:119], v[188:191], v[2:5]
	v_mfma_f32_16x16x32_bf16 v[54:57], v[112:115], v[168:171], v[54:57]
	v_mfma_f32_16x16x32_bf16 v[50:53], v[124:127], v[168:171], v[50:53]
	v_mfma_f32_16x16x32_bf16 v[38:41], v[112:115], v[176:179], v[38:41]
	v_mfma_f32_16x16x32_bf16 v[34:37], v[124:127], v[176:179], v[34:37]
	v_mfma_f32_16x16x32_bf16 v[22:25], v[112:115], v[184:187], v[22:25]
	v_mfma_f32_16x16x32_bf16 v[18:21], v[124:127], v[184:187], v[18:21]
	v_mfma_f32_16x16x32_bf16 v[6:9], v[112:115], v[192:195], v[6:9]
	v_mfma_f32_16x16x32_bf16 v[2:5], v[124:127], v[192:195], v[2:5]
	s_barrier
	s_mov_b32 s100, 0
	s_add_i32 s96, s96, 2
	s_add_u32 s56, s56, 0x100
	s_addc_u32 s57, s57, 0
	s_add_u32 s95, s95, 0x100
	s_addc_u32 vcc_lo, vcc_lo, 0
	s_cmp_gt_u32 s96, 13
	s_cbranch_scc0 .LBB0_908
	s_setprio 0
	s_mov_b32 s100, 1
	v_mov_b32_e32 v196, 0x2d00
	v_mov_b32_e32 v231, 0x2400
	v_mov_b32_e32 v228, 0x1b00
	s_and_b64 vcc, exec, s[0:1]
	s_movk_i32 s21, 0x4000
	s_cbranch_vccz .LBB0_911
	s_barrier

.LBB0_1010:
	s_ashr_i32 s21, s20, 31
	s_lshl_b64 s[4:5], s[20:21], 19
	s_add_u32 s30, s22, s4
	s_addc_u32 s31, s23, s5
	s_and_b64 s[4:5], s[36:37], exec
	s_cselect_b32 s21, s31, s41
	s_cselect_b32 s88, s30, s40
	s_ashr_i32 s15, s14, 31
	s_lshl_b64 s[4:5], s[14:15], 19
	s_add_u32 s38, s18, s4
	s_addc_u32 s39, s27, s5
	s_and_b64 s[4:5], s[36:37], exec
	s_cselect_b32 s15, s39, s57
	s_cselect_b32 s89, s38, s56
	s_add_u32 s40, s40, 0x40080
	s_addc_u32 s41, s41, 0
	s_add_u32 s90, s56, 0x100
	v_mov_b32_e32 v2, 0
	s_addc_u32 s91, s57, 0
	s_mov_b32 s92, -2
	v_mov_b32_e32 v3, v2
	v_mov_b32_e32 v4, v2
	v_mov_b32_e32 v5, v2
	v_mov_b32_e32 v6, v2
	v_mov_b32_e32 v7, v2
	v_mov_b32_e32 v8, v2
	v_mov_b32_e32 v9, v2
	v_mov_b32_e32 v18, v2
	v_mov_b32_e32 v19, v2
	v_mov_b32_e32 v20, v2
	v_mov_b32_e32 v21, v2
	v_mov_b32_e32 v22, v2
	v_mov_b32_e32 v23, v2
	v_mov_b32_e32 v24, v2
	v_mov_b32_e32 v25, v2
	v_mov_b32_e32 v34, v2
	v_mov_b32_e32 v35, v2
	v_mov_b32_e32 v36, v2
	v_mov_b32_e32 v37, v2
	v_mov_b32_e32 v38, v2
	v_mov_b32_e32 v39, v2
	v_mov_b32_e32 v40, v2
	v_mov_b32_e32 v41, v2
	v_mov_b32_e32 v50, v2
	v_mov_b32_e32 v51, v2
	v_mov_b32_e32 v52, v2
	v_mov_b32_e32 v53, v2
	v_mov_b32_e32 v54, v2
	v_mov_b32_e32 v55, v2
	v_mov_b32_e32 v56, v2
	v_mov_b32_e32 v57, v2
	v_mov_b32_e32 v10, v2
	v_mov_b32_e32 v11, v2
	v_mov_b32_e32 v12, v2
	v_mov_b32_e32 v13, v2
	v_mov_b32_e32 v14, v2
	v_mov_b32_e32 v15, v2
	v_mov_b32_e32 v16, v2
	v_mov_b32_e32 v17, v2
	v_mov_b32_e32 v26, v2
	v_mov_b32_e32 v27, v2
	v_mov_b32_e32 v28, v2
	v_mov_b32_e32 v29, v2
	v_mov_b32_e32 v30, v2
	v_mov_b32_e32 v31, v2
	v_mov_b32_e32 v32, v2
	v_mov_b32_e32 v33, v2
	v_mov_b32_e32 v42, v2
	v_mov_b32_e32 v43, v2
	v_mov_b32_e32 v44, v2
	v_mov_b32_e32 v45, v2
	v_mov_b32_e32 v46, v2
	v_mov_b32_e32 v47, v2
	v_mov_b32_e32 v48, v2
	v_mov_b32_e32 v49, v2
	v_mov_b32_e32 v58, v2
	v_mov_b32_e32 v59, v2
	v_mov_b32_e32 v60, v2
	v_mov_b32_e32 v61, v2
	v_mov_b32_e32 v62, v2
	v_mov_b32_e32 v63, v2
	v_mov_b32_e32 v64, v2
	v_mov_b32_e32 v65, v2
	v_mov_b32_e32 v66, v2
	v_mov_b32_e32 v67, v2
	v_mov_b32_e32 v68, v2
	v_mov_b32_e32 v69, v2
	v_mov_b32_e32 v70, v2
	v_mov_b32_e32 v71, v2
	v_mov_b32_e32 v72, v2
	v_mov_b32_e32 v73, v2
	v_mov_b32_e32 v82, v2
	v_mov_b32_e32 v83, v2
	v_mov_b32_e32 v84, v2
	v_mov_b32_e32 v85, v2
	v_mov_b32_e32 v86, v2
	v_mov_b32_e32 v87, v2
	v_mov_b32_e32 v88, v2
	v_mov_b32_e32 v89, v2
	v_mov_b32_e32 v100, v2
	v_mov_b32_e32 v101, v2
	v_mov_b32_e32 v102, v2
	v_mov_b32_e32 v103, v2
	v_mov_b32_e32 v104, v2
	v_mov_b32_e32 v105, v2
	v_mov_b32_e32 v106, v2
	v_mov_b32_e32 v107, v2
	v_mov_b32_e32 v116, v2
	v_mov_b32_e32 v117, v2
	v_mov_b32_e32 v118, v2
	v_mov_b32_e32 v119, v2
	v_mov_b32_e32 v120, v2
	v_mov_b32_e32 v121, v2
	v_mov_b32_e32 v122, v2
	v_mov_b32_e32 v123, v2
	v_mov_b32_e32 v74, v2
	v_mov_b32_e32 v75, v2
	v_mov_b32_e32 v76, v2
	v_mov_b32_e32 v77, v2
	v_mov_b32_e32 v78, v2
	v_mov_b32_e32 v79, v2
	v_mov_b32_e32 v80, v2
	v_mov_b32_e32 v81, v2
	v_mov_b32_e32 v90, v2
	v_mov_b32_e32 v91, v2
	v_mov_b32_e32 v92, v2
	v_mov_b32_e32 v93, v2
	v_mov_b32_e32 v94, v2
	v_mov_b32_e32 v95, v2
	v_mov_b32_e32 v96, v2
	v_mov_b32_e32 v97, v2
	v_mov_b32_e32 v108, v2
	v_mov_b32_e32 v109, v2
	v_mov_b32_e32 v110, v2
	v_mov_b32_e32 v111, v2
	v_mov_b32_e32 v112, v2
	v_mov_b32_e32 v113, v2
	v_mov_b32_e32 v114, v2
	v_mov_b32_e32 v115, v2
	v_mov_b32_e32 v124, v2
	v_mov_b32_e32 v125, v2
	v_mov_b32_e32 v126, v2
	v_mov_b32_e32 v127, v2
	v_mov_b32_e32 v128, v2
	v_mov_b32_e32 v129, v2
	v_mov_b32_e32 v130, v2
	v_mov_b32_e32 v131, v2
	s_bitcmp1_b32 s70, 12
	s_cbranch_scc0 .Lmy_sp_g3
	s_setprio 1
.Lmy_sp_g3:
.LBB0_1011:
	s_add_u32 s4, s40, 0xfffc0080
	s_addc_u32 s5, s41, -1
	s_add_i32 s6, 0, 0x10000
	s_cmp_eq_u32 s92, 12
	s_cselect_b32 s69, s21, s5
	s_cselect_b32 s68, s88, s4
	s_cselect_b32 s57, s15, s91
	s_cselect_b32 s56, s89, s90
	s_add_i32 s7, 0, 0x14000
	v_add_u32_e32 v144, s6, v189
	v_add_u32_e32 v160, s7, v189
	ds_read_b128 v[132:135], v144
	ds_read_b128 v[136:139], v144 offset:1024
	ds_read_b128 v[140:143], v144 offset:2048
	ds_read_b128 v[144:147], v144 offset:3072
	ds_read_b128 v[156:159], v160
	ds_read_b128 v[162:165], v160 offset:1024
	ds_read_b128 v[192:195], v160 offset:2048
	ds_read_b128 v[200:203], v160 offset:3072
	s_add_i32 s44, s70, 0
	v_lshl_add_u64 v[166:167], s[40:41], 0, v[98:99]
	s_add_i32 m0, s44, 0xc000
	ds_read_b128 v[204:207], v191
	ds_read_b128 v[208:211], v191 offset:1024
	ds_read_b128 v[212:215], v191 offset:2048
	ds_read_b128 v[216:219], v191 offset:3072
	ds_read_b128 v[220:223], v191 offset:4096
	ds_read_b128 v[224:227], v191 offset:5120
	ds_read_b128 v[238:241], v191 offset:6144
	ds_read_b128 v[242:245], v191 offset:7168
	global_load_lds_dwordx4 v[166:167], off
	v_lshl_add_u64 v[166:167], s[40:41], 0, v[150:151]
	s_add_i32 m0, s44, 0xe000
	s_nop 0
	global_load_lds_dwordx4 v[166:167], off
	s_cmp_eq_u32 s100, 1
	s_cbranch_scc1 .Lmy_sk7
	s_waitcnt vmcnt(8)
.Lmy_sk7:
	s_waitcnt lgkmcnt(0)
	s_barrier
	v_mfma_f32_16x16x32_bf16 v[128:131], v[132:135], v[204:207], v[128:131]
	v_mfma_f32_16x16x32_bf16 v[124:127], v[140:143], v[204:207], v[124:127]
	v_mfma_f32_16x16x32_bf16 v[112:115], v[132:135], v[212:215], v[112:115]
	v_mfma_f32_16x16x32_bf16 v[108:111], v[140:143], v[212:215], v[108:111]
	v_mfma_f32_16x16x32_bf16 v[94:97], v[132:135], v[220:223], v[94:97]
	v_mfma_f32_16x16x32_bf16 v[90:93], v[140:143], v[220:223], v[90:93]
	v_mfma_f32_16x16x32_bf16 v[78:81], v[132:135], v[238:241], v[78:81]
	v_mfma_f32_16x16x32_bf16 v[74:77], v[140:143], v[238:241], v[74:77]
	v_mfma_f32_16x16x32_bf16 v[128:131], v[136:139], v[208:211], v[128:131]
	v_mfma_f32_16x16x32_bf16 v[124:127], v[144:147], v[208:211], v[124:127]
	v_mfma_f32_16x16x32_bf16 v[112:115], v[136:139], v[216:219], v[112:115]
	v_mfma_f32_16x16x32_bf16 v[108:111], v[144:147], v[216:219], v[108:111]
	v_mfma_f32_16x16x32_bf16 v[94:97], v[136:139], v[224:227], v[94:97]
	v_mfma_f32_16x16x32_bf16 v[90:93], v[144:147], v[224:227], v[90:93]
	v_mfma_f32_16x16x32_bf16 v[78:81], v[136:139], v[242:245], v[78:81]
	v_mfma_f32_16x16x32_bf16 v[74:77], v[144:147], v[242:245], v[74:77]
	v_mfma_f32_16x16x32_bf16 v[120:123], v[156:159], v[204:207], v[120:123]
	v_mfma_f32_16x16x32_bf16 v[116:119], v[192:195], v[204:207], v[116:119]
	v_mfma_f32_16x16x32_bf16 v[104:107], v[156:159], v[212:215], v[104:107]
	v_mfma_f32_16x16x32_bf16 v[100:103], v[192:195], v[212:215], v[100:103]
	v_mfma_f32_16x16x32_bf16 v[86:89], v[156:159], v[220:223], v[86:89]
	v_mfma_f32_16x16x32_bf16 v[82:85], v[192:195], v[220:223], v[82:85]
	v_mfma_f32_16x16x32_bf16 v[70:73], v[156:159], v[238:241], v[70:73]
	v_mfma_f32_16x16x32_bf16 v[66:69], v[192:195], v[238:241], v[66:69]
	v_mfma_f32_16x16x32_bf16 v[120:123], v[162:165], v[208:211], v[120:123]
	v_mfma_f32_16x16x32_bf16 v[116:119], v[200:203], v[208:211], v[116:119]
	v_mfma_f32_16x16x32_bf16 v[104:107], v[162:165], v[216:219], v[104:107]
	v_mfma_f32_16x16x32_bf16 v[100:103], v[200:203], v[216:219], v[100:103]
	v_mfma_f32_16x16x32_bf16 v[86:89], v[162:165], v[224:227], v[86:89]
	v_mfma_f32_16x16x32_bf16 v[82:85], v[200:203], v[224:227], v[82:85]
	v_mfma_f32_16x16x32_bf16 v[70:73], v[162:165], v[242:245], v[70:73]
	v_mfma_f32_16x16x32_bf16 v[66:69], v[200:203], v[242:245], v[66:69]
	s_barrier
	s_add_i32 s4, s6, s70
	v_lshl_add_u64 v[166:167], s[56:57], 0, v[148:149]
	s_mov_b32 m0, s4
	ds_read_b128 v[204:207], v191 offset:16384
	ds_read_b128 v[208:211], v191 offset:17408
	ds_read_b128 v[212:215], v191 offset:18432
	ds_read_b128 v[216:219], v191 offset:19456
	ds_read_b128 v[220:223], v191 offset:20480
	ds_read_b128 v[224:227], v191 offset:21504
	ds_read_b128 v[238:241], v191 offset:22528
	ds_read_b128 v[242:245], v191 offset:23552
	global_load_lds_dwordx4 v[166:167], off
	s_add_i32 m0, s4, 0x2000
	s_add_u32 s4, s56, 0x40000
	v_lshl_add_u64 v[170:171], s[56:57], 0, v[152:153]
	s_addc_u32 s5, s57, 0
	s_add_i32 s6, s7, s70
	global_load_lds_dwordx4 v[170:171], off
	v_lshl_add_u64 v[176:177], s[4:5], 0, v[148:149]
	s_mov_b32 m0, s6
	v_lshl_add_u64 v[180:181], s[68:69], 0, v[150:151]
	global_load_lds_dwordx4 v[176:177], off
	v_lshl_add_u64 v[176:177], s[4:5], 0, v[152:153]
	s_add_i32 m0, s6, 0x2000
	s_nop 0
	global_load_lds_dwordx4 v[176:177], off
	v_lshl_add_u64 v[176:177], s[68:69], 0, v[98:99]
	s_mov_b32 m0, s44
	s_nop 0
	global_load_lds_dwordx4 v[176:177], off
	s_add_i32 m0, s44, 0x2000
	s_nop 0
	global_load_lds_dwordx4 v[180:181], off
	s_cmp_eq_u32 s100, 1
	s_cbranch_scc1 .Lmy_sk8
	s_waitcnt vmcnt(8)
.Lmy_sk8:
	s_waitcnt lgkmcnt(0)
	s_barrier
	v_mfma_f32_16x16x32_bf16 v[62:65], v[132:135], v[204:207], v[62:65]
	v_mfma_f32_16x16x32_bf16 v[58:61], v[140:143], v[204:207], v[58:61]
	v_mfma_f32_16x16x32_bf16 v[46:49], v[132:135], v[212:215], v[46:49]
	v_mfma_f32_16x16x32_bf16 v[42:45], v[140:143], v[212:215], v[42:45]
	v_mfma_f32_16x16x32_bf16 v[30:33], v[132:135], v[220:223], v[30:33]
	v_mfma_f32_16x16x32_bf16 v[26:29], v[140:143], v[220:223], v[26:29]
	v_mfma_f32_16x16x32_bf16 v[14:17], v[132:135], v[238:241], v[14:17]
	v_mfma_f32_16x16x32_bf16 v[10:13], v[140:143], v[238:241], v[10:13]
	v_mfma_f32_16x16x32_bf16 v[62:65], v[136:139], v[208:211], v[62:65]
	v_mfma_f32_16x16x32_bf16 v[58:61], v[144:147], v[208:211], v[58:61]
	v_mfma_f32_16x16x32_bf16 v[46:49], v[136:139], v[216:219], v[46:49]
	v_mfma_f32_16x16x32_bf16 v[42:45], v[144:147], v[216:219], v[42:45]
	v_mfma_f32_16x16x32_bf16 v[30:33], v[136:139], v[224:227], v[30:33]
	v_mfma_f32_16x16x32_bf16 v[26:29], v[144:147], v[224:227], v[26:29]
	v_mfma_f32_16x16x32_bf16 v[14:17], v[136:139], v[242:245], v[14:17]
	v_mfma_f32_16x16x32_bf16 v[10:13], v[144:147], v[242:245], v[10:13]
	v_mfma_f32_16x16x32_bf16 v[54:57], v[156:159], v[204:207], v[54:57]
	v_mfma_f32_16x16x32_bf16 v[50:53], v[192:195], v[204:207], v[50:53]
	v_mfma_f32_16x16x32_bf16 v[38:41], v[156:159], v[212:215], v[38:41]
	v_mfma_f32_16x16x32_bf16 v[34:37], v[192:195], v[212:215], v[34:37]
	v_mfma_f32_16x16x32_bf16 v[22:25], v[156:159], v[220:223], v[22:25]
	v_mfma_f32_16x16x32_bf16 v[18:21], v[192:195], v[220:223], v[18:21]
	v_mfma_f32_16x16x32_bf16 v[6:9], v[156:159], v[238:241], v[6:9]
	v_mfma_f32_16x16x32_bf16 v[2:5], v[192:195], v[238:241], v[2:5]
	v_mfma_f32_16x16x32_bf16 v[54:57], v[162:165], v[208:211], v[54:57]
	v_mfma_f32_16x16x32_bf16 v[50:53], v[200:203], v[208:211], v[50:53]
	v_mfma_f32_16x16x32_bf16 v[38:41], v[162:165], v[216:219], v[38:41]
	v_mfma_f32_16x16x32_bf16 v[34:37], v[200:203], v[216:219], v[34:37]
	v_mfma_f32_16x16x32_bf16 v[22:25], v[162:165], v[224:227], v[22:25]
	v_mfma_f32_16x16x32_bf16 v[18:21], v[200:203], v[224:227], v[18:21]
	v_mfma_f32_16x16x32_bf16 v[6:9], v[162:165], v[242:245], v[6:9]
	v_mfma_f32_16x16x32_bf16 v[2:5], v[200:203], v[242:245], v[2:5]
	s_barrier
	s_add_i32 s6, 0, 0x18000
	s_add_i32 s7, 0, 0x1c000
	v_add_u32_e32 v144, s6, v189
	v_add_u32_e32 v160, s7, v189
	ds_read_b128 v[132:135], v144
	ds_read_b128 v[136:139], v144 offset:1024
	ds_read_b128 v[140:143], v144 offset:2048
	ds_read_b128 v[144:147], v144 offset:3072
	ds_read_b128 v[156:159], v160
	ds_read_b128 v[162:165], v160 offset:1024
	ds_read_b128 v[192:195], v160 offset:2048
	ds_read_b128 v[200:203], v160 offset:3072
	s_add_u32 s4, s68, 0x40000
	s_addc_u32 s5, s69, 0
	v_lshl_add_u64 v[246:247], s[4:5], 0, v[98:99]
	s_add_i32 m0, s44, 0x4000
	ds_read_b128 v[204:207], v191 offset:32768
	ds_read_b128 v[208:211], v191 offset:33792
	ds_read_b128 v[212:215], v191 offset:34816
	ds_read_b128 v[216:219], v191 offset:35840
	ds_read_b128 v[220:223], v191 offset:36864
	ds_read_b128 v[224:227], v191 offset:37888
	ds_read_b128 v[238:241], v191 offset:38912
	ds_read_b128 v[242:245], v191 offset:39936
	global_load_lds_dwordx4 v[246:247], off
	v_lshl_add_u64 v[246:247], s[4:5], 0, v[150:151]
	s_add_i32 m0, s44, 0x6000
	s_nop 0
	global_load_lds_dwordx4 v[246:247], off
	s_waitcnt vmcnt(8)
	s_waitcnt lgkmcnt(0)
	s_barrier
	v_mfma_f32_16x16x32_bf16 v[128:131], v[132:135], v[204:207], v[128:131]
	v_mfma_f32_16x16x32_bf16 v[124:127], v[140:143], v[204:207], v[124:127]
	v_mfma_f32_16x16x32_bf16 v[112:115], v[132:135], v[212:215], v[112:115]
	v_mfma_f32_16x16x32_bf16 v[108:111], v[140:143], v[212:215], v[108:111]
	v_mfma_f32_16x16x32_bf16 v[94:97], v[132:135], v[220:223], v[94:97]
	v_mfma_f32_16x16x32_bf16 v[90:93], v[140:143], v[220:223], v[90:93]
	v_mfma_f32_16x16x32_bf16 v[78:81], v[132:135], v[238:241], v[78:81]
	v_mfma_f32_16x16x32_bf16 v[74:77], v[140:143], v[238:241], v[74:77]
	v_mfma_f32_16x16x32_bf16 v[128:131], v[136:139], v[208:211], v[128:131]
	v_mfma_f32_16x16x32_bf16 v[124:127], v[144:147], v[208:211], v[124:127]
	v_mfma_f32_16x16x32_bf16 v[112:115], v[136:139], v[216:219], v[112:115]
	v_mfma_f32_16x16x32_bf16 v[108:111], v[144:147], v[216:219], v[108:111]
	v_mfma_f32_16x16x32_bf16 v[94:97], v[136:139], v[224:227], v[94:97]
	v_mfma_f32_16x16x32_bf16 v[90:93], v[144:147], v[224:227], v[90:93]
	v_mfma_f32_16x16x32_bf16 v[78:81], v[136:139], v[242:245], v[78:81]
	v_mfma_f32_16x16x32_bf16 v[74:77], v[144:147], v[242:245], v[74:77]
	v_mfma_f32_16x16x32_bf16 v[120:123], v[156:159], v[204:207], v[120:123]
	v_mfma_f32_16x16x32_bf16 v[116:119], v[192:195], v[204:207], v[116:119]
	v_mfma_f32_16x16x32_bf16 v[104:107], v[156:159], v[212:215], v[104:107]
	v_mfma_f32_16x16x32_bf16 v[100:103], v[192:195], v[212:215], v[100:103]
	v_mfma_f32_16x16x32_bf16 v[86:89], v[156:159], v[220:223], v[86:89]
	v_mfma_f32_16x16x32_bf16 v[82:85], v[192:195], v[220:223], v[82:85]
	v_mfma_f32_16x16x32_bf16 v[70:73], v[156:159], v[238:241], v[70:73]
	v_mfma_f32_16x16x32_bf16 v[66:69], v[192:195], v[238:241], v[66:69]
	v_mfma_f32_16x16x32_bf16 v[120:123], v[162:165], v[208:211], v[120:123]
	v_mfma_f32_16x16x32_bf16 v[116:119], v[200:203], v[208:211], v[116:119]
	v_mfma_f32_16x16x32_bf16 v[104:107], v[162:165], v[216:219], v[104:107]
	v_mfma_f32_16x16x32_bf16 v[100:103], v[200:203], v[216:219], v[100:103]
	v_mfma_f32_16x16x32_bf16 v[86:89], v[162:165], v[224:227], v[86:89]
	v_mfma_f32_16x16x32_bf16 v[82:85], v[200:203], v[224:227], v[82:85]
	v_mfma_f32_16x16x32_bf16 v[70:73], v[162:165], v[242:245], v[70:73]
	v_mfma_f32_16x16x32_bf16 v[66:69], v[200:203], v[242:245], v[66:69]
	s_barrier
	s_add_i32 s4, s6, s70
	v_lshl_add_u64 v[166:167], v[166:167], 0, s[42:43]
	s_mov_b32 m0, s4
	ds_read_b128 v[204:207], v191 offset:49152
	ds_read_b128 v[208:211], v191 offset:50176
	ds_read_b128 v[212:215], v191 offset:51200
	ds_read_b128 v[216:219], v191 offset:52224
	ds_read_b128 v[220:223], v191 offset:53248
	ds_read_b128 v[224:227], v191 offset:54272
	ds_read_b128 v[238:241], v191 offset:55296
	ds_read_b128 v[242:245], v191 offset:56320
	global_load_lds_dwordx4 v[166:167], off
	s_add_i32 m0, s4, 0x2000
	s_add_u32 s4, s56, 0x40080
	v_lshl_add_u64 v[166:167], v[170:171], 0, s[42:43]
	s_addc_u32 s5, s57, 0
	s_add_i32 s6, s7, s70
	global_load_lds_dwordx4 v[166:167], off
	v_lshl_add_u64 v[166:167], s[4:5], 0, v[148:149]
	s_mov_b32 m0, s6
	s_nop 0
	global_load_lds_dwordx4 v[166:167], off
	v_lshl_add_u64 v[166:167], s[4:5], 0, v[152:153]
	s_add_i32 m0, s6, 0x2000
	s_nop 0
	global_load_lds_dwordx4 v[166:167], off
	v_lshl_add_u64 v[166:167], v[176:177], 0, s[42:43]
	s_add_i32 m0, s44, 0x8000
	s_nop 0
	global_load_lds_dwordx4 v[166:167], off
	v_lshl_add_u64 v[166:167], v[180:181], 0, s[42:43]
	s_add_i32 m0, s44, 0xa000
	s_nop 0
	global_load_lds_dwordx4 v[166:167], off
	s_waitcnt vmcnt(8)
	s_waitcnt lgkmcnt(0)
	s_barrier
	v_mfma_f32_16x16x32_bf16 v[62:65], v[132:135], v[204:207], v[62:65]
	v_mfma_f32_16x16x32_bf16 v[58:61], v[140:143], v[204:207], v[58:61]
	v_mfma_f32_16x16x32_bf16 v[46:49], v[132:135], v[212:215], v[46:49]
	v_mfma_f32_16x16x32_bf16 v[42:45], v[140:143], v[212:215], v[42:45]
	v_mfma_f32_16x16x32_bf16 v[30:33], v[132:135], v[220:223], v[30:33]
	v_mfma_f32_16x16x32_bf16 v[26:29], v[140:143], v[220:223], v[26:29]
	v_mfma_f32_16x16x32_bf16 v[14:17], v[132:135], v[238:241], v[14:17]
	v_mfma_f32_16x16x32_bf16 v[10:13], v[140:143], v[238:241], v[10:13]
	v_mfma_f32_16x16x32_bf16 v[62:65], v[136:139], v[208:211], v[62:65]
	v_mfma_f32_16x16x32_bf16 v[58:61], v[144:147], v[208:211], v[58:61]
	v_mfma_f32_16x16x32_bf16 v[46:49], v[136:139], v[216:219], v[46:49]
	v_mfma_f32_16x16x32_bf16 v[42:45], v[144:147], v[216:219], v[42:45]
	v_mfma_f32_16x16x32_bf16 v[30:33], v[136:139], v[224:227], v[30:33]
	v_mfma_f32_16x16x32_bf16 v[26:29], v[144:147], v[224:227], v[26:29]
	v_mfma_f32_16x16x32_bf16 v[14:17], v[136:139], v[242:245], v[14:17]
	v_mfma_f32_16x16x32_bf16 v[10:13], v[144:147], v[242:245], v[10:13]
	v_mfma_f32_16x16x32_bf16 v[54:57], v[156:159], v[204:207], v[54:57]
	v_mfma_f32_16x16x32_bf16 v[50:53], v[192:195], v[204:207], v[50:53]
	v_mfma_f32_16x16x32_bf16 v[38:41], v[156:159], v[212:215], v[38:41]
	v_mfma_f32_16x16x32_bf16 v[34:37], v[192:195], v[212:215], v[34:37]
	v_mfma_f32_16x16x32_bf16 v[22:25], v[156:159], v[220:223], v[22:25]
	v_mfma_f32_16x16x32_bf16 v[18:21], v[192:195], v[220:223], v[18:21]
	v_mfma_f32_16x16x32_bf16 v[6:9], v[156:159], v[238:241], v[6:9]
	v_mfma_f32_16x16x32_bf16 v[2:5], v[192:195], v[238:241], v[2:5]
	v_mfma_f32_16x16x32_bf16 v[54:57], v[162:165], v[208:211], v[54:57]
	v_mfma_f32_16x16x32_bf16 v[50:53], v[200:203], v[208:211], v[50:53]
	v_mfma_f32_16x16x32_bf16 v[38:41], v[162:165], v[216:219], v[38:41]
	v_mfma_f32_16x16x32_bf16 v[34:37], v[200:203], v[216:219], v[34:37]
	v_mfma_f32_16x16x32_bf16 v[22:25], v[162:165], v[224:227], v[22:25]
	v_mfma_f32_16x16x32_bf16 v[18:21], v[200:203], v[224:227], v[18:21]
	v_mfma_f32_16x16x32_bf16 v[6:9], v[162:165], v[242:245], v[6:9]
	v_mfma_f32_16x16x32_bf16 v[2:5], v[200:203], v[242:245], v[2:5]
	s_barrier
	s_mov_b32 s100, 0
	s_add_i32 s92, s92, 2
	s_add_u32 s40, s40, 0x100
	s_addc_u32 s41, s41, 0
	s_add_u32 s90, s90, 0x100
	s_addc_u32 s91, s91, 0
	s_cmp_gt_u32 s92, 13
	s_cbranch_scc0 .LBB0_1011
	s_setprio 0
	s_mov_b32 s100, 1
	s_and_b64 vcc, exec, s[0:1]
	s_cbranch_vccz .LBB0_1014
	s_barrier

.LBB0_1115:
	s_ashr_i32 s27, s26, 31
	s_lshl_b64 s[4:5], s[26:27], 21
	s_add_u32 s40, s24, s4
	s_addc_u32 s41, s25, s5
	s_and_b64 s[4:5], s[30:31], exec
	s_cselect_b32 s18, s41, s75
	s_cselect_b32 s21, s40, s74
	s_ashr_i32 s69, s68, 31
	s_lshl_b64 s[4:5], s[68:69], 21
	s_add_u32 s56, s77, s4
	s_addc_u32 s57, s88, s5
	s_and_b64 s[4:5], s[30:31], exec
	s_cselect_b32 s27, s57, s79
	s_cselect_b32 s69, s56, s78
	s_add_u32 s74, s74, 0x100080
	s_addc_u32 s75, s75, 0
	s_add_u32 s71, s78, 0x100
	v_mov_b32_e32 v2, 0
	s_addc_u32 s94, s79, 0
	s_mov_b32 s95, -2
	s_waitcnt lgkmcnt(0)
	v_mov_b32_e32 v3, v2
	v_mov_b32_e32 v4, v2
	v_mov_b32_e32 v5, v2
	v_mov_b32_e32 v6, v2
	v_mov_b32_e32 v7, v2
	v_mov_b32_e32 v8, v2
	v_mov_b32_e32 v9, v2
	v_mov_b32_e32 v18, v2
	v_mov_b32_e32 v19, v2
	v_mov_b32_e32 v20, v2
	v_mov_b32_e32 v21, v2
	v_mov_b32_e32 v22, v2
	v_mov_b32_e32 v23, v2
	v_mov_b32_e32 v24, v2
	v_mov_b32_e32 v25, v2
	v_mov_b32_e32 v34, v2
	v_mov_b32_e32 v35, v2
	v_mov_b32_e32 v36, v2
	v_mov_b32_e32 v37, v2
	v_mov_b32_e32 v38, v2
	v_mov_b32_e32 v39, v2
	v_mov_b32_e32 v40, v2
	v_mov_b32_e32 v41, v2
	v_mov_b32_e32 v50, v2
	v_mov_b32_e32 v51, v2
	v_mov_b32_e32 v52, v2
	v_mov_b32_e32 v53, v2
	v_mov_b32_e32 v54, v2
	v_mov_b32_e32 v55, v2
	v_mov_b32_e32 v56, v2
	v_mov_b32_e32 v57, v2
	v_mov_b32_e32 v10, v2
	v_mov_b32_e32 v11, v2
	v_mov_b32_e32 v12, v2
	v_mov_b32_e32 v13, v2
	v_mov_b32_e32 v14, v2
	v_mov_b32_e32 v15, v2
	v_mov_b32_e32 v16, v2
	v_mov_b32_e32 v17, v2
	v_mov_b32_e32 v26, v2
	v_mov_b32_e32 v27, v2
	v_mov_b32_e32 v28, v2
	v_mov_b32_e32 v29, v2
	v_mov_b32_e32 v30, v2
	v_mov_b32_e32 v31, v2
	v_mov_b32_e32 v32, v2
	v_mov_b32_e32 v33, v2
	v_mov_b32_e32 v42, v2
	v_mov_b32_e32 v43, v2
	v_mov_b32_e32 v44, v2
	v_mov_b32_e32 v45, v2
	v_mov_b32_e32 v46, v2
	v_mov_b32_e32 v47, v2
	v_mov_b32_e32 v48, v2
	v_mov_b32_e32 v49, v2
	v_mov_b32_e32 v58, v2
	v_mov_b32_e32 v59, v2
	v_mov_b32_e32 v60, v2
	v_mov_b32_e32 v61, v2
	v_mov_b32_e32 v62, v2
	v_mov_b32_e32 v63, v2
	v_mov_b32_e32 v64, v2
	v_mov_b32_e32 v65, v2
	v_mov_b32_e32 v66, v2
	v_mov_b32_e32 v67, v2
	v_mov_b32_e32 v68, v2
	v_mov_b32_e32 v69, v2
	v_mov_b32_e32 v70, v2
	v_mov_b32_e32 v71, v2
	v_mov_b32_e32 v72, v2
	v_mov_b32_e32 v73, v2
	v_mov_b32_e32 v82, v2
	v_mov_b32_e32 v83, v2
	v_mov_b32_e32 v84, v2
	v_mov_b32_e32 v85, v2
	v_mov_b32_e32 v86, v2
	v_mov_b32_e32 v87, v2
	v_mov_b32_e32 v88, v2
	v_mov_b32_e32 v89, v2
	v_mov_b32_e32 v100, v2
	v_mov_b32_e32 v101, v2
	v_mov_b32_e32 v102, v2
	v_mov_b32_e32 v103, v2
	v_mov_b32_e32 v104, v2
	v_mov_b32_e32 v105, v2
	v_mov_b32_e32 v106, v2
	v_mov_b32_e32 v107, v2
	v_mov_b32_e32 v132, v2
	v_mov_b32_e32 v133, v2
	v_mov_b32_e32 v134, v2
	v_mov_b32_e32 v135, v2
	v_mov_b32_e32 v136, v2
	v_mov_b32_e32 v137, v2
	v_mov_b32_e32 v138, v2
	v_mov_b32_e32 v139, v2
	v_mov_b32_e32 v74, v2
	v_mov_b32_e32 v75, v2
	v_mov_b32_e32 v76, v2
	v_mov_b32_e32 v77, v2
	v_mov_b32_e32 v78, v2
	v_mov_b32_e32 v79, v2
	v_mov_b32_e32 v80, v2
	v_mov_b32_e32 v81, v2
	v_mov_b32_e32 v90, v2
	v_mov_b32_e32 v91, v2
	v_mov_b32_e32 v92, v2
	v_mov_b32_e32 v93, v2
	v_mov_b32_e32 v94, v2
	v_mov_b32_e32 v95, v2
	v_mov_b32_e32 v96, v2
	v_mov_b32_e32 v97, v2
	v_mov_b32_e32 v108, v2
	v_mov_b32_e32 v109, v2
	v_mov_b32_e32 v110, v2
	v_mov_b32_e32 v111, v2
	v_mov_b32_e32 v120, v2
	v_mov_b32_e32 v121, v2
	v_mov_b32_e32 v122, v2
	v_mov_b32_e32 v123, v2
	v_mov_b32_e32 v140, v2
	v_mov_b32_e32 v141, v2
	v_mov_b32_e32 v142, v2
	v_mov_b32_e32 v143, v2
	v_mov_b32_e32 v144, v2
	v_mov_b32_e32 v145, v2
	v_mov_b32_e32 v146, v2
	v_mov_b32_e32 v147, v2
	s_bitcmp1_b32 s91, 12
	s_cbranch_scc0 .Lmy_sp_g4a
	s_setprio 1
.Lmy_sp_g4a:
.LBB0_1116:
	s_add_u32 s4, s74, 0xfff00080
	s_addc_u32 s5, s75, -1
	s_add_i32 s6, 0, 0x10000
	s_cmp_eq_u32 s95, 60
	s_cselect_b32 vcc_hi, s18, s5
	s_cselect_b32 vcc_lo, s21, s4
	s_cselect_b32 s79, s27, s94
	s_cselect_b32 s78, s69, s71
	s_add_i32 s7, 0, 0x14000
	v_add_u32_e32 v128, s6, v205
	v_add_u32_e32 v160, s7, v205
	ds_read_b128 v[112:115], v128
	ds_read_b128 v[116:119], v128 offset:1024
	ds_read_b128 v[124:127], v128 offset:2048
	ds_read_b128 v[128:131], v128 offset:3072
	ds_read_b128 v[148:151], v160
	ds_read_b128 v[152:155], v160 offset:1024
	ds_read_b128 v[156:159], v160 offset:2048
	ds_read_b128 v[160:163], v160 offset:3072
	s_add_i32 s44, s91, 0
	v_lshl_add_u64 v[194:195], s[74:75], 0, v[98:99]
	s_add_i32 m0, s44, 0xc000
	ds_read_b128 v[164:167], v207
	ds_read_b128 v[168:171], v207 offset:1024
	ds_read_b128 v[178:181], v207 offset:2048
	ds_read_b128 v[182:185], v207 offset:3072
	ds_read_b128 v[186:189], v207 offset:4096
	ds_read_b128 v[190:193], v207 offset:5120
	ds_read_b128 v[200:203], v207 offset:6144
	ds_read_b128 v[208:211], v207 offset:7168
	global_load_lds_dwordx4 v[194:195], off
	v_lshl_add_u64 v[194:195], s[74:75], 0, v[174:175]
	s_add_i32 m0, s44, 0xe000
	s_nop 0
	global_load_lds_dwordx4 v[194:195], off
	s_cmp_eq_u32 s100, 1
	s_cbranch_scc1 .Lmy_sk9
	s_waitcnt vmcnt(8)
.Lmy_sk9:
	s_waitcnt lgkmcnt(0)
	s_barrier
	v_mfma_f32_16x16x32_bf16 v[144:147], v[112:115], v[164:167], v[144:147]
	v_mfma_f32_16x16x32_bf16 v[140:143], v[124:127], v[164:167], v[140:143]
	v_mfma_f32_16x16x32_bf16 v[120:123], v[112:115], v[178:181], v[120:123]
	v_mfma_f32_16x16x32_bf16 v[108:111], v[124:127], v[178:181], v[108:111]
	v_mfma_f32_16x16x32_bf16 v[94:97], v[112:115], v[186:189], v[94:97]
	v_mfma_f32_16x16x32_bf16 v[90:93], v[124:127], v[186:189], v[90:93]
	v_mfma_f32_16x16x32_bf16 v[78:81], v[112:115], v[200:203], v[78:81]
	v_mfma_f32_16x16x32_bf16 v[74:77], v[124:127], v[200:203], v[74:77]
	v_mfma_f32_16x16x32_bf16 v[144:147], v[116:119], v[168:171], v[144:147]
	v_mfma_f32_16x16x32_bf16 v[140:143], v[128:131], v[168:171], v[140:143]
	v_mfma_f32_16x16x32_bf16 v[120:123], v[116:119], v[182:185], v[120:123]
	v_mfma_f32_16x16x32_bf16 v[108:111], v[128:131], v[182:185], v[108:111]
	v_mfma_f32_16x16x32_bf16 v[94:97], v[116:119], v[190:193], v[94:97]
	v_mfma_f32_16x16x32_bf16 v[90:93], v[128:131], v[190:193], v[90:93]
	v_mfma_f32_16x16x32_bf16 v[78:81], v[116:119], v[208:211], v[78:81]
	v_mfma_f32_16x16x32_bf16 v[74:77], v[128:131], v[208:211], v[74:77]
	v_mfma_f32_16x16x32_bf16 v[136:139], v[148:151], v[164:167], v[136:139]
	v_mfma_f32_16x16x32_bf16 v[132:135], v[156:159], v[164:167], v[132:135]
	v_mfma_f32_16x16x32_bf16 v[104:107], v[148:151], v[178:181], v[104:107]
	v_mfma_f32_16x16x32_bf16 v[100:103], v[156:159], v[178:181], v[100:103]
	v_mfma_f32_16x16x32_bf16 v[86:89], v[148:151], v[186:189], v[86:89]
	v_mfma_f32_16x16x32_bf16 v[82:85], v[156:159], v[186:189], v[82:85]
	v_mfma_f32_16x16x32_bf16 v[70:73], v[148:151], v[200:203], v[70:73]
	v_mfma_f32_16x16x32_bf16 v[66:69], v[156:159], v[200:203], v[66:69]
	v_mfma_f32_16x16x32_bf16 v[136:139], v[152:155], v[168:171], v[136:139]
	v_mfma_f32_16x16x32_bf16 v[132:135], v[160:163], v[168:171], v[132:135]
	v_mfma_f32_16x16x32_bf16 v[104:107], v[152:155], v[182:185], v[104:107]
	v_mfma_f32_16x16x32_bf16 v[100:103], v[160:163], v[182:185], v[100:103]
	v_mfma_f32_16x16x32_bf16 v[86:89], v[152:155], v[190:193], v[86:89]
	v_mfma_f32_16x16x32_bf16 v[82:85], v[160:163], v[190:193], v[82:85]
	v_mfma_f32_16x16x32_bf16 v[70:73], v[152:155], v[208:211], v[70:73]
	v_mfma_f32_16x16x32_bf16 v[66:69], v[160:163], v[208:211], v[66:69]
	s_barrier
	s_add_i32 s4, s6, s91
	v_lshl_add_u64 v[194:195], s[78:79], 0, v[172:173]
	s_mov_b32 m0, s4
	ds_read_b128 v[164:167], v207 offset:16384
	ds_read_b128 v[168:171], v207 offset:17408
	ds_read_b128 v[178:181], v207 offset:18432
	ds_read_b128 v[182:185], v207 offset:19456
	ds_read_b128 v[186:189], v207 offset:20480
	ds_read_b128 v[190:193], v207 offset:21504
	ds_read_b128 v[200:203], v207 offset:22528
	ds_read_b128 v[208:211], v207 offset:23552
	global_load_lds_dwordx4 v[194:195], off
	s_add_i32 m0, s4, 0x2000
	s_add_u32 s4, s78, 0x100000
	v_lshl_add_u64 v[212:213], s[78:79], 0, v[176:177]
	s_addc_u32 s5, s79, 0
	s_add_i32 s6, s7, s91
	global_load_lds_dwordx4 v[212:213], off
	v_lshl_add_u64 v[214:215], s[4:5], 0, v[172:173]
	s_mov_b32 m0, s6
	v_lshl_add_u64 v[216:217], vcc, 0, v[174:175]
	global_load_lds_dwordx4 v[214:215], off
	v_lshl_add_u64 v[214:215], s[4:5], 0, v[176:177]
	s_add_i32 m0, s6, 0x2000
	s_nop 0
	global_load_lds_dwordx4 v[214:215], off
	v_lshl_add_u64 v[214:215], vcc, 0, v[98:99]
	s_mov_b32 m0, s44
	s_nop 0
	global_load_lds_dwordx4 v[214:215], off
	s_add_i32 m0, s44, 0x2000
	s_nop 0
	global_load_lds_dwordx4 v[216:217], off
	s_cmp_eq_u32 s100, 1
	s_cbranch_scc1 .Lmy_sk10
	s_waitcnt vmcnt(8)
.Lmy_sk10:
	s_waitcnt lgkmcnt(0)
	s_barrier
	v_mfma_f32_16x16x32_bf16 v[62:65], v[112:115], v[164:167], v[62:65]
	v_mfma_f32_16x16x32_bf16 v[58:61], v[124:127], v[164:167], v[58:61]
	v_mfma_f32_16x16x32_bf16 v[46:49], v[112:115], v[178:181], v[46:49]
	v_mfma_f32_16x16x32_bf16 v[42:45], v[124:127], v[178:181], v[42:45]
	v_mfma_f32_16x16x32_bf16 v[30:33], v[112:115], v[186:189], v[30:33]
	v_mfma_f32_16x16x32_bf16 v[26:29], v[124:127], v[186:189], v[26:29]
	v_mfma_f32_16x16x32_bf16 v[14:17], v[112:115], v[200:203], v[14:17]
	v_mfma_f32_16x16x32_bf16 v[10:13], v[124:127], v[200:203], v[10:13]
	v_mfma_f32_16x16x32_bf16 v[62:65], v[116:119], v[168:171], v[62:65]
	v_mfma_f32_16x16x32_bf16 v[58:61], v[128:131], v[168:171], v[58:61]
	v_mfma_f32_16x16x32_bf16 v[46:49], v[116:119], v[182:185], v[46:49]
	v_mfma_f32_16x16x32_bf16 v[42:45], v[128:131], v[182:185], v[42:45]
	v_mfma_f32_16x16x32_bf16 v[30:33], v[116:119], v[190:193], v[30:33]
	v_mfma_f32_16x16x32_bf16 v[26:29], v[128:131], v[190:193], v[26:29]
	v_mfma_f32_16x16x32_bf16 v[14:17], v[116:119], v[208:211], v[14:17]
	v_mfma_f32_16x16x32_bf16 v[10:13], v[128:131], v[208:211], v[10:13]
	v_mfma_f32_16x16x32_bf16 v[54:57], v[148:151], v[164:167], v[54:57]
	v_mfma_f32_16x16x32_bf16 v[50:53], v[156:159], v[164:167], v[50:53]
	v_mfma_f32_16x16x32_bf16 v[38:41], v[148:151], v[178:181], v[38:41]
	v_mfma_f32_16x16x32_bf16 v[34:37], v[156:159], v[178:181], v[34:37]
	v_mfma_f32_16x16x32_bf16 v[22:25], v[148:151], v[186:189], v[22:25]
	v_mfma_f32_16x16x32_bf16 v[18:21], v[156:159], v[186:189], v[18:21]
	v_mfma_f32_16x16x32_bf16 v[6:9], v[148:151], v[200:203], v[6:9]
	v_mfma_f32_16x16x32_bf16 v[2:5], v[156:159], v[200:203], v[2:5]
	v_mfma_f32_16x16x32_bf16 v[54:57], v[152:155], v[168:171], v[54:57]
	v_mfma_f32_16x16x32_bf16 v[50:53], v[160:163], v[168:171], v[50:53]
	v_mfma_f32_16x16x32_bf16 v[38:41], v[152:155], v[182:185], v[38:41]
	v_mfma_f32_16x16x32_bf16 v[34:37], v[160:163], v[182:185], v[34:37]
	v_mfma_f32_16x16x32_bf16 v[22:25], v[152:155], v[190:193], v[22:25]
	v_mfma_f32_16x16x32_bf16 v[18:21], v[160:163], v[190:193], v[18:21]
	v_mfma_f32_16x16x32_bf16 v[6:9], v[152:155], v[208:211], v[6:9]
	v_mfma_f32_16x16x32_bf16 v[2:5], v[160:163], v[208:211], v[2:5]
	s_barrier
	s_add_i32 s6, 0, 0x18000
	s_add_i32 s7, 0, 0x1c000
	v_add_u32_e32 v128, s6, v205
	v_add_u32_e32 v160, s7, v205
	ds_read_b128 v[112:115], v128
	ds_read_b128 v[116:119], v128 offset:1024
	ds_read_b128 v[124:127], v128 offset:2048
	ds_read_b128 v[128:131], v128 offset:3072
	ds_read_b128 v[148:151], v160
	ds_read_b128 v[152:155], v160 offset:1024
	ds_read_b128 v[156:159], v160 offset:2048
	ds_read_b128 v[160:163], v160 offset:3072
	s_add_u32 s4, vcc_lo, 0x100000
	s_addc_u32 s5, vcc_hi, 0
	v_lshl_add_u64 v[218:219], s[4:5], 0, v[98:99]
	s_add_i32 m0, s44, 0x4000
	ds_read_b128 v[164:167], v207 offset:32768
	ds_read_b128 v[168:171], v207 offset:33792
	ds_read_b128 v[178:181], v207 offset:34816
	ds_read_b128 v[182:185], v207 offset:35840
	ds_read_b128 v[186:189], v207 offset:36864
	ds_read_b128 v[190:193], v207 offset:37888
	ds_read_b128 v[200:203], v207 offset:38912
	ds_read_b128 v[208:211], v207 offset:39936
	global_load_lds_dwordx4 v[218:219], off
	v_lshl_add_u64 v[218:219], s[4:5], 0, v[174:175]
	s_add_i32 m0, s44, 0x6000
	s_nop 0
	global_load_lds_dwordx4 v[218:219], off
	s_waitcnt vmcnt(8)
	s_waitcnt lgkmcnt(0)
	s_barrier
	v_mfma_f32_16x16x32_bf16 v[144:147], v[112:115], v[164:167], v[144:147]
	v_mfma_f32_16x16x32_bf16 v[140:143], v[124:127], v[164:167], v[140:143]
	v_mfma_f32_16x16x32_bf16 v[120:123], v[112:115], v[178:181], v[120:123]
	v_mfma_f32_16x16x32_bf16 v[108:111], v[124:127], v[178:181], v[108:111]
	v_mfma_f32_16x16x32_bf16 v[94:97], v[112:115], v[186:189], v[94:97]
	v_mfma_f32_16x16x32_bf16 v[90:93], v[124:127], v[186:189], v[90:93]
	v_mfma_f32_16x16x32_bf16 v[78:81], v[112:115], v[200:203], v[78:81]
	v_mfma_f32_16x16x32_bf16 v[74:77], v[124:127], v[200:203], v[74:77]
	v_mfma_f32_16x16x32_bf16 v[144:147], v[116:119], v[168:171], v[144:147]
	v_mfma_f32_16x16x32_bf16 v[140:143], v[128:131], v[168:171], v[140:143]
	v_mfma_f32_16x16x32_bf16 v[120:123], v[116:119], v[182:185], v[120:123]
	v_mfma_f32_16x16x32_bf16 v[108:111], v[128:131], v[182:185], v[108:111]
	v_mfma_f32_16x16x32_bf16 v[94:97], v[116:119], v[190:193], v[94:97]
	v_mfma_f32_16x16x32_bf16 v[90:93], v[128:131], v[190:193], v[90:93]
	v_mfma_f32_16x16x32_bf16 v[78:81], v[116:119], v[208:211], v[78:81]
	v_mfma_f32_16x16x32_bf16 v[74:77], v[128:131], v[208:211], v[74:77]
	v_mfma_f32_16x16x32_bf16 v[136:139], v[148:151], v[164:167], v[136:139]
	v_mfma_f32_16x16x32_bf16 v[132:135], v[156:159], v[164:167], v[132:135]
	v_mfma_f32_16x16x32_bf16 v[104:107], v[148:151], v[178:181], v[104:107]
	v_mfma_f32_16x16x32_bf16 v[100:103], v[156:159], v[178:181], v[100:103]
	v_mfma_f32_16x16x32_bf16 v[86:89], v[148:151], v[186:189], v[86:89]
	v_mfma_f32_16x16x32_bf16 v[82:85], v[156:159], v[186:189], v[82:85]
	v_mfma_f32_16x16x32_bf16 v[70:73], v[148:151], v[200:203], v[70:73]
	v_mfma_f32_16x16x32_bf16 v[66:69], v[156:159], v[200:203], v[66:69]
	v_mfma_f32_16x16x32_bf16 v[136:139], v[152:155], v[168:171], v[136:139]
	v_mfma_f32_16x16x32_bf16 v[132:135], v[160:163], v[168:171], v[132:135]
	v_mfma_f32_16x16x32_bf16 v[104:107], v[152:155], v[182:185], v[104:107]
	v_mfma_f32_16x16x32_bf16 v[100:103], v[160:163], v[182:185], v[100:103]
	v_mfma_f32_16x16x32_bf16 v[86:89], v[152:155], v[190:193], v[86:89]
	v_mfma_f32_16x16x32_bf16 v[82:85], v[160:163], v[190:193], v[82:85]
	v_mfma_f32_16x16x32_bf16 v[70:73], v[152:155], v[208:211], v[70:73]
	v_mfma_f32_16x16x32_bf16 v[66:69], v[160:163], v[208:211], v[66:69]
	s_barrier
	s_add_i32 s4, s6, s91
	v_lshl_add_u64 v[194:195], v[194:195], 0, s[42:43]
	s_mov_b32 m0, s4
	ds_read_b128 v[164:167], v207 offset:49152
	ds_read_b128 v[168:171], v207 offset:50176
	ds_read_b128 v[178:181], v207 offset:51200
	ds_read_b128 v[182:185], v207 offset:52224
	ds_read_b128 v[186:189], v207 offset:53248
	ds_read_b128 v[190:193], v207 offset:54272
	ds_read_b128 v[200:203], v207 offset:55296
	ds_read_b128 v[208:211], v207 offset:56320
	global_load_lds_dwordx4 v[194:195], off
	s_add_i32 m0, s4, 0x2000
	s_add_u32 s4, s78, 0x100080
	v_lshl_add_u64 v[194:195], v[212:213], 0, s[42:43]
	s_addc_u32 s5, s79, 0
	s_add_i32 s6, s7, s91
	global_load_lds_dwordx4 v[194:195], off
	v_lshl_add_u64 v[194:195], s[4:5], 0, v[172:173]
	s_mov_b32 m0, s6
	s_nop 0
	global_load_lds_dwordx4 v[194:195], off
	v_lshl_add_u64 v[194:195], s[4:5], 0, v[176:177]
	s_add_i32 m0, s6, 0x2000
	s_nop 0
	global_load_lds_dwordx4 v[194:195], off
	v_lshl_add_u64 v[194:195], v[214:215], 0, s[42:43]
	s_add_i32 m0, s44, 0x8000
	s_nop 0
	global_load_lds_dwordx4 v[194:195], off
	v_lshl_add_u64 v[194:195], v[216:217], 0, s[42:43]
	s_add_i32 m0, s44, 0xa000
	s_nop 0
	global_load_lds_dwordx4 v[194:195], off
	s_waitcnt vmcnt(8)
	s_waitcnt lgkmcnt(0)
	s_barrier
	v_mfma_f32_16x16x32_bf16 v[62:65], v[112:115], v[164:167], v[62:65]
	v_mfma_f32_16x16x32_bf16 v[58:61], v[124:127], v[164:167], v[58:61]
	v_mfma_f32_16x16x32_bf16 v[46:49], v[112:115], v[178:181], v[46:49]
	v_mfma_f32_16x16x32_bf16 v[42:45], v[124:127], v[178:181], v[42:45]
	v_mfma_f32_16x16x32_bf16 v[30:33], v[112:115], v[186:189], v[30:33]
	v_mfma_f32_16x16x32_bf16 v[26:29], v[124:127], v[186:189], v[26:29]
	v_mfma_f32_16x16x32_bf16 v[14:17], v[112:115], v[200:203], v[14:17]
	v_mfma_f32_16x16x32_bf16 v[10:13], v[124:127], v[200:203], v[10:13]
	v_mfma_f32_16x16x32_bf16 v[62:65], v[116:119], v[168:171], v[62:65]
	v_mfma_f32_16x16x32_bf16 v[58:61], v[128:131], v[168:171], v[58:61]
	v_mfma_f32_16x16x32_bf16 v[46:49], v[116:119], v[182:185], v[46:49]
	v_mfma_f32_16x16x32_bf16 v[42:45], v[128:131], v[182:185], v[42:45]
	v_mfma_f32_16x16x32_bf16 v[30:33], v[116:119], v[190:193], v[30:33]
	v_mfma_f32_16x16x32_bf16 v[26:29], v[128:131], v[190:193], v[26:29]
	v_mfma_f32_16x16x32_bf16 v[14:17], v[116:119], v[208:211], v[14:17]
	v_mfma_f32_16x16x32_bf16 v[10:13], v[128:131], v[208:211], v[10:13]
	v_mfma_f32_16x16x32_bf16 v[54:57], v[148:151], v[164:167], v[54:57]
	v_mfma_f32_16x16x32_bf16 v[50:53], v[156:159], v[164:167], v[50:53]
	v_mfma_f32_16x16x32_bf16 v[38:41], v[148:151], v[178:181], v[38:41]
	v_mfma_f32_16x16x32_bf16 v[34:37], v[156:159], v[178:181], v[34:37]
	v_mfma_f32_16x16x32_bf16 v[22:25], v[148:151], v[186:189], v[22:25]
	v_mfma_f32_16x16x32_bf16 v[18:21], v[156:159], v[186:189], v[18:21]
	v_mfma_f32_16x16x32_bf16 v[6:9], v[148:151], v[200:203], v[6:9]
	v_mfma_f32_16x16x32_bf16 v[2:5], v[156:159], v[200:203], v[2:5]
	v_mfma_f32_16x16x32_bf16 v[54:57], v[152:155], v[168:171], v[54:57]
	v_mfma_f32_16x16x32_bf16 v[50:53], v[160:163], v[168:171], v[50:53]
	v_mfma_f32_16x16x32_bf16 v[38:41], v[152:155], v[182:185], v[38:41]
	v_mfma_f32_16x16x32_bf16 v[34:37], v[160:163], v[182:185], v[34:37]
	v_mfma_f32_16x16x32_bf16 v[22:25], v[152:155], v[190:193], v[22:25]
	v_mfma_f32_16x16x32_bf16 v[18:21], v[160:163], v[190:193], v[18:21]
	v_mfma_f32_16x16x32_bf16 v[6:9], v[152:155], v[208:211], v[6:9]
	v_mfma_f32_16x16x32_bf16 v[2:5], v[160:163], v[208:211], v[2:5]
	s_barrier
	s_mov_b32 s100, 0
	s_add_i32 s95, s95, 2
	s_add_u32 s74, s74, 0x100
	s_addc_u32 s75, s75, 0
	s_add_u32 s71, s71, 0x100
	s_addc_u32 s94, s94, 0
	s_cmp_gt_u32 s95, 61
	s_cbranch_scc0 .LBB0_1116
	s_setprio 0
	s_mov_b32 s100, 1
	s_and_b64 vcc, exec, s[10:11]
	s_cbranch_vccz .LBB0_1119
	s_barrier

.LBB0_1171:
	s_ashr_i32 s27, s26, 31
	s_lshl_b64 s[4:5], s[26:27], 21
	s_add_u32 s40, s24, s4
	s_addc_u32 s41, s25, s5
	s_and_b64 s[4:5], s[30:31], exec
	s_cselect_b32 s18, s41, s71
	s_cselect_b32 s27, s40, s70
	s_ashr_i32 s15, s14, 31
	s_lshl_b64 s[4:5], s[14:15], 21
	s_add_u32 s20, s77, s4
	s_addc_u32 s21, s88, s5
	s_and_b64 s[4:5], s[30:31], exec
	s_cselect_b32 s15, s21, s75
	s_cselect_b32 s57, s20, s74
	s_add_u32 s70, s70, 0x100080
	s_addc_u32 s71, s71, 0
	s_add_u32 s69, s74, 0x100
	v_mov_b32_e32 v2, 0
	s_addc_u32 s94, s75, 0
	s_mov_b32 s95, -2
	s_waitcnt lgkmcnt(0)
	v_mov_b32_e32 v3, v2
	v_mov_b32_e32 v4, v2
	v_mov_b32_e32 v5, v2
	v_mov_b32_e32 v6, v2
	v_mov_b32_e32 v7, v2
	v_mov_b32_e32 v8, v2
	v_mov_b32_e32 v9, v2
	v_mov_b32_e32 v18, v2
	v_mov_b32_e32 v19, v2
	v_mov_b32_e32 v20, v2
	v_mov_b32_e32 v21, v2
	v_mov_b32_e32 v22, v2
	v_mov_b32_e32 v23, v2
	v_mov_b32_e32 v24, v2
	v_mov_b32_e32 v25, v2
	v_mov_b32_e32 v34, v2
	v_mov_b32_e32 v35, v2
	v_mov_b32_e32 v36, v2
	v_mov_b32_e32 v37, v2
	v_mov_b32_e32 v38, v2
	v_mov_b32_e32 v39, v2
	v_mov_b32_e32 v40, v2
	v_mov_b32_e32 v41, v2
	v_mov_b32_e32 v50, v2
	v_mov_b32_e32 v51, v2
	v_mov_b32_e32 v52, v2
	v_mov_b32_e32 v53, v2
	v_mov_b32_e32 v54, v2
	v_mov_b32_e32 v55, v2
	v_mov_b32_e32 v56, v2
	v_mov_b32_e32 v57, v2
	v_mov_b32_e32 v10, v2
	v_mov_b32_e32 v11, v2
	v_mov_b32_e32 v12, v2
	v_mov_b32_e32 v13, v2
	v_mov_b32_e32 v14, v2
	v_mov_b32_e32 v15, v2
	v_mov_b32_e32 v16, v2
	v_mov_b32_e32 v17, v2
	v_mov_b32_e32 v26, v2
	v_mov_b32_e32 v27, v2
	v_mov_b32_e32 v28, v2
	v_mov_b32_e32 v29, v2
	v_mov_b32_e32 v30, v2
	v_mov_b32_e32 v31, v2
	v_mov_b32_e32 v32, v2
	v_mov_b32_e32 v33, v2
	v_mov_b32_e32 v42, v2
	v_mov_b32_e32 v43, v2
	v_mov_b32_e32 v44, v2
	v_mov_b32_e32 v45, v2
	v_mov_b32_e32 v46, v2
	v_mov_b32_e32 v47, v2
	v_mov_b32_e32 v48, v2
	v_mov_b32_e32 v49, v2
	v_mov_b32_e32 v58, v2
	v_mov_b32_e32 v59, v2
	v_mov_b32_e32 v60, v2
	v_mov_b32_e32 v61, v2
	v_mov_b32_e32 v62, v2
	v_mov_b32_e32 v63, v2
	v_mov_b32_e32 v64, v2
	v_mov_b32_e32 v65, v2
	v_mov_b32_e32 v66, v2
	v_mov_b32_e32 v67, v2
	v_mov_b32_e32 v68, v2
	v_mov_b32_e32 v69, v2
	v_mov_b32_e32 v70, v2
	v_mov_b32_e32 v71, v2
	v_mov_b32_e32 v72, v2
	v_mov_b32_e32 v73, v2
	v_mov_b32_e32 v82, v2
	v_mov_b32_e32 v83, v2
	v_mov_b32_e32 v84, v2
	v_mov_b32_e32 v85, v2
	v_mov_b32_e32 v86, v2
	v_mov_b32_e32 v87, v2
	v_mov_b32_e32 v88, v2
	v_mov_b32_e32 v89, v2
	v_mov_b32_e32 v132, v2
	v_mov_b32_e32 v133, v2
	v_mov_b32_e32 v134, v2
	v_mov_b32_e32 v135, v2
	v_mov_b32_e32 v136, v2
	v_mov_b32_e32 v137, v2
	v_mov_b32_e32 v138, v2
	v_mov_b32_e32 v139, v2
	v_mov_b32_e32 v148, v2
	v_mov_b32_e32 v149, v2
	v_mov_b32_e32 v150, v2
	v_mov_b32_e32 v151, v2
	v_mov_b32_e32 v152, v2
	v_mov_b32_e32 v153, v2
	v_mov_b32_e32 v154, v2
	v_mov_b32_e32 v155, v2
	v_mov_b32_e32 v74, v2
	v_mov_b32_e32 v75, v2
	v_mov_b32_e32 v76, v2
	v_mov_b32_e32 v77, v2
	v_mov_b32_e32 v78, v2
	v_mov_b32_e32 v79, v2
	v_mov_b32_e32 v80, v2
	v_mov_b32_e32 v81, v2
	v_mov_b32_e32 v116, v2
	v_mov_b32_e32 v117, v2
	v_mov_b32_e32 v118, v2
	v_mov_b32_e32 v119, v2
	v_mov_b32_e32 v124, v2
	v_mov_b32_e32 v125, v2
	v_mov_b32_e32 v126, v2
	v_mov_b32_e32 v127, v2
	v_mov_b32_e32 v140, v2
	v_mov_b32_e32 v141, v2
	v_mov_b32_e32 v142, v2
	v_mov_b32_e32 v143, v2
	v_mov_b32_e32 v144, v2
	v_mov_b32_e32 v145, v2
	v_mov_b32_e32 v146, v2
	v_mov_b32_e32 v147, v2
	v_mov_b32_e32 v156, v2
	v_mov_b32_e32 v157, v2
	v_mov_b32_e32 v158, v2
	v_mov_b32_e32 v159, v2
	v_mov_b32_e32 v160, v2
	v_mov_b32_e32 v161, v2
	v_mov_b32_e32 v162, v2
	v_mov_b32_e32 v163, v2
	s_bitcmp1_b32 s91, 12
	s_cbranch_scc0 .Lmy_sp_g4b
	s_setprio 1
.Lmy_sp_g4b:
.LBB0_1172:
	s_add_u32 s4, s70, 0xfff00080
	s_addc_u32 s5, s71, -1
	s_add_i32 s6, 0, 0x10000
	s_cmp_eq_u32 s95, 60
	s_cselect_b32 s79, s18, s5
	s_cselect_b32 s78, s27, s4
	s_cselect_b32 s75, s15, s94
	s_cselect_b32 s74, s57, s69
	s_add_i32 s7, 0, 0x14000
	v_add_u32_e32 v104, s6, v239
	v_add_u32_e32 v128, s7, v239
	ds_read_b128 v[90:93], v104
	ds_read_b128 v[94:97], v104 offset:1024
	ds_read_b128 v[100:103], v104 offset:2048
	ds_read_b128 v[104:107], v104 offset:3072
	ds_read_b128 v[108:111], v128
	ds_read_b128 v[112:115], v128 offset:1024
	ds_read_b128 v[120:123], v128 offset:2048
	ds_read_b128 v[128:131], v128 offset:3072
	s_add_i32 s44, s91, 0
	v_lshl_add_u64 v[200:201], s[70:71], 0, v[98:99]
	s_add_i32 m0, s44, 0xc000
	ds_read_b128 v[164:167], v241
	ds_read_b128 v[168:171], v241 offset:1024
	ds_read_b128 v[172:175], v241 offset:2048
	ds_read_b128 v[176:179], v241 offset:3072
	ds_read_b128 v[180:183], v241 offset:4096
	ds_read_b128 v[184:187], v241 offset:5120
	ds_read_b128 v[188:191], v241 offset:6144
	ds_read_b128 v[192:195], v241 offset:7168
	global_load_lds_dwordx4 v[200:201], off
	v_lshl_add_u64 v[200:201], s[70:71], 0, v[206:207]
	s_add_i32 m0, s44, 0xe000
	s_nop 0
	global_load_lds_dwordx4 v[200:201], off
	s_cmp_eq_u32 s100, 1
	s_cbranch_scc1 .Lmy_sk11
	s_waitcnt vmcnt(8)
.Lmy_sk11:
	s_waitcnt lgkmcnt(0)
	s_barrier
	v_mfma_f32_16x16x32_bf16 v[160:163], v[90:93], v[164:167], v[160:163]
	v_mfma_f32_16x16x32_bf16 v[156:159], v[100:103], v[164:167], v[156:159]
	v_mfma_f32_16x16x32_bf16 v[144:147], v[90:93], v[172:175], v[144:147]
	v_mfma_f32_16x16x32_bf16 v[140:143], v[100:103], v[172:175], v[140:143]
	v_mfma_f32_16x16x32_bf16 v[124:127], v[90:93], v[180:183], v[124:127]
	v_mfma_f32_16x16x32_bf16 v[116:119], v[100:103], v[180:183], v[116:119]
	v_mfma_f32_16x16x32_bf16 v[78:81], v[90:93], v[188:191], v[78:81]
	v_mfma_f32_16x16x32_bf16 v[74:77], v[100:103], v[188:191], v[74:77]
	v_mfma_f32_16x16x32_bf16 v[160:163], v[94:97], v[168:171], v[160:163]
	v_mfma_f32_16x16x32_bf16 v[156:159], v[104:107], v[168:171], v[156:159]
	v_mfma_f32_16x16x32_bf16 v[144:147], v[94:97], v[176:179], v[144:147]
	v_mfma_f32_16x16x32_bf16 v[140:143], v[104:107], v[176:179], v[140:143]
	v_mfma_f32_16x16x32_bf16 v[124:127], v[94:97], v[184:187], v[124:127]
	v_mfma_f32_16x16x32_bf16 v[116:119], v[104:107], v[184:187], v[116:119]
	v_mfma_f32_16x16x32_bf16 v[78:81], v[94:97], v[192:195], v[78:81]
	v_mfma_f32_16x16x32_bf16 v[74:77], v[104:107], v[192:195], v[74:77]
	v_mfma_f32_16x16x32_bf16 v[152:155], v[108:111], v[164:167], v[152:155]
	v_mfma_f32_16x16x32_bf16 v[148:151], v[120:123], v[164:167], v[148:151]
	v_mfma_f32_16x16x32_bf16 v[136:139], v[108:111], v[172:175], v[136:139]
	v_mfma_f32_16x16x32_bf16 v[132:135], v[120:123], v[172:175], v[132:135]
	v_mfma_f32_16x16x32_bf16 v[86:89], v[108:111], v[180:183], v[86:89]
	v_mfma_f32_16x16x32_bf16 v[82:85], v[120:123], v[180:183], v[82:85]
	v_mfma_f32_16x16x32_bf16 v[70:73], v[108:111], v[188:191], v[70:73]
	v_mfma_f32_16x16x32_bf16 v[66:69], v[120:123], v[188:191], v[66:69]
	v_mfma_f32_16x16x32_bf16 v[152:155], v[112:115], v[168:171], v[152:155]
	v_mfma_f32_16x16x32_bf16 v[148:151], v[128:131], v[168:171], v[148:151]
	v_mfma_f32_16x16x32_bf16 v[136:139], v[112:115], v[176:179], v[136:139]
	v_mfma_f32_16x16x32_bf16 v[132:135], v[128:131], v[176:179], v[132:135]
	v_mfma_f32_16x16x32_bf16 v[86:89], v[112:115], v[184:187], v[86:89]
	v_mfma_f32_16x16x32_bf16 v[82:85], v[128:131], v[184:187], v[82:85]
	v_mfma_f32_16x16x32_bf16 v[70:73], v[112:115], v[192:195], v[70:73]
	v_mfma_f32_16x16x32_bf16 v[66:69], v[128:131], v[192:195], v[66:69]
	s_barrier
	s_add_i32 s4, s6, s91
	v_lshl_add_u64 v[200:201], s[74:75], 0, v[204:205]
	s_mov_b32 m0, s4
	ds_read_b128 v[164:167], v241 offset:16384
	ds_read_b128 v[168:171], v241 offset:17408
	ds_read_b128 v[172:175], v241 offset:18432
	ds_read_b128 v[176:179], v241 offset:19456
	ds_read_b128 v[180:183], v241 offset:20480
	ds_read_b128 v[184:187], v241 offset:21504
	ds_read_b128 v[188:191], v241 offset:22528
	ds_read_b128 v[192:195], v241 offset:23552
	global_load_lds_dwordx4 v[200:201], off
	s_add_i32 m0, s4, 0x2000
	s_add_u32 s4, s74, 0x100000
	v_lshl_add_u64 v[202:203], s[74:75], 0, v[208:209]
	s_addc_u32 s5, s75, 0
	s_add_i32 s6, s7, s91
	global_load_lds_dwordx4 v[202:203], off
	v_lshl_add_u64 v[210:211], s[4:5], 0, v[204:205]
	s_mov_b32 m0, s6
	v_lshl_add_u64 v[212:213], s[78:79], 0, v[206:207]
	global_load_lds_dwordx4 v[210:211], off
	v_lshl_add_u64 v[210:211], s[4:5], 0, v[208:209]
	s_add_i32 m0, s6, 0x2000
	s_nop 0
	global_load_lds_dwordx4 v[210:211], off
	v_lshl_add_u64 v[210:211], s[78:79], 0, v[98:99]
	s_mov_b32 m0, s44
	s_nop 0
	global_load_lds_dwordx4 v[210:211], off
	s_add_i32 m0, s44, 0x2000
	s_nop 0
	global_load_lds_dwordx4 v[212:213], off
	s_cmp_eq_u32 s100, 1
	s_cbranch_scc1 .Lmy_sk12
	s_waitcnt vmcnt(8)
.Lmy_sk12:
	s_waitcnt lgkmcnt(0)
	s_barrier
	v_mfma_f32_16x16x32_bf16 v[62:65], v[90:93], v[164:167], v[62:65]
	v_mfma_f32_16x16x32_bf16 v[58:61], v[100:103], v[164:167], v[58:61]
	v_mfma_f32_16x16x32_bf16 v[46:49], v[90:93], v[172:175], v[46:49]
	v_mfma_f32_16x16x32_bf16 v[42:45], v[100:103], v[172:175], v[42:45]
	v_mfma_f32_16x16x32_bf16 v[30:33], v[90:93], v[180:183], v[30:33]
	v_mfma_f32_16x16x32_bf16 v[26:29], v[100:103], v[180:183], v[26:29]
	v_mfma_f32_16x16x32_bf16 v[14:17], v[90:93], v[188:191], v[14:17]
	v_mfma_f32_16x16x32_bf16 v[10:13], v[100:103], v[188:191], v[10:13]
	v_mfma_f32_16x16x32_bf16 v[62:65], v[94:97], v[168:171], v[62:65]
	v_mfma_f32_16x16x32_bf16 v[58:61], v[104:107], v[168:171], v[58:61]
	v_mfma_f32_16x16x32_bf16 v[46:49], v[94:97], v[176:179], v[46:49]
	v_mfma_f32_16x16x32_bf16 v[42:45], v[104:107], v[176:179], v[42:45]
	v_mfma_f32_16x16x32_bf16 v[30:33], v[94:97], v[184:187], v[30:33]
	v_mfma_f32_16x16x32_bf16 v[26:29], v[104:107], v[184:187], v[26:29]
	v_mfma_f32_16x16x32_bf16 v[14:17], v[94:97], v[192:195], v[14:17]
	v_mfma_f32_16x16x32_bf16 v[10:13], v[104:107], v[192:195], v[10:13]
	v_mfma_f32_16x16x32_bf16 v[54:57], v[108:111], v[164:167], v[54:57]
	v_mfma_f32_16x16x32_bf16 v[50:53], v[120:123], v[164:167], v[50:53]
	v_mfma_f32_16x16x32_bf16 v[38:41], v[108:111], v[172:175], v[38:41]
	v_mfma_f32_16x16x32_bf16 v[34:37], v[120:123], v[172:175], v[34:37]
	v_mfma_f32_16x16x32_bf16 v[22:25], v[108:111], v[180:183], v[22:25]
	v_mfma_f32_16x16x32_bf16 v[18:21], v[120:123], v[180:183], v[18:21]
	v_mfma_f32_16x16x32_bf16 v[6:9], v[108:111], v[188:191], v[6:9]
	v_mfma_f32_16x16x32_bf16 v[2:5], v[120:123], v[188:191], v[2:5]
	v_mfma_f32_16x16x32_bf16 v[54:57], v[112:115], v[168:171], v[54:57]
	v_mfma_f32_16x16x32_bf16 v[50:53], v[128:131], v[168:171], v[50:53]
	v_mfma_f32_16x16x32_bf16 v[38:41], v[112:115], v[176:179], v[38:41]
	v_mfma_f32_16x16x32_bf16 v[34:37], v[128:131], v[176:179], v[34:37]
	v_mfma_f32_16x16x32_bf16 v[22:25], v[112:115], v[184:187], v[22:25]
	v_mfma_f32_16x16x32_bf16 v[18:21], v[128:131], v[184:187], v[18:21]
	v_mfma_f32_16x16x32_bf16 v[6:9], v[112:115], v[192:195], v[6:9]
	v_mfma_f32_16x16x32_bf16 v[2:5], v[128:131], v[192:195], v[2:5]
	s_barrier
	s_add_i32 s6, 0, 0x18000
	s_add_i32 s7, 0, 0x1c000
	v_add_u32_e32 v104, s6, v239
	v_add_u32_e32 v128, s7, v239
	ds_read_b128 v[90:93], v104
	ds_read_b128 v[94:97], v104 offset:1024
	ds_read_b128 v[100:103], v104 offset:2048
	ds_read_b128 v[104:107], v104 offset:3072
	ds_read_b128 v[108:111], v128
	ds_read_b128 v[112:115], v128 offset:1024
	ds_read_b128 v[120:123], v128 offset:2048
	ds_read_b128 v[128:131], v128 offset:3072
	s_add_u32 s4, s78, 0x100000
	s_addc_u32 s5, s79, 0
	v_lshl_add_u64 v[214:215], s[4:5], 0, v[98:99]
	s_add_i32 m0, s44, 0x4000
	ds_read_b128 v[164:167], v241 offset:32768
	ds_read_b128 v[168:171], v241 offset:33792
	ds_read_b128 v[172:175], v241 offset:34816
	ds_read_b128 v[176:179], v241 offset:35840
	ds_read_b128 v[180:183], v241 offset:36864
	ds_read_b128 v[184:187], v241 offset:37888
	ds_read_b128 v[188:191], v241 offset:38912
	ds_read_b128 v[192:195], v241 offset:39936
	global_load_lds_dwordx4 v[214:215], off
	v_lshl_add_u64 v[214:215], s[4:5], 0, v[206:207]
	s_add_i32 m0, s44, 0x6000
	s_nop 0
	global_load_lds_dwordx4 v[214:215], off
	s_waitcnt vmcnt(8)
	s_waitcnt lgkmcnt(0)
	s_barrier
	v_mfma_f32_16x16x32_bf16 v[160:163], v[90:93], v[164:167], v[160:163]
	v_mfma_f32_16x16x32_bf16 v[156:159], v[100:103], v[164:167], v[156:159]
	v_mfma_f32_16x16x32_bf16 v[144:147], v[90:93], v[172:175], v[144:147]
	v_mfma_f32_16x16x32_bf16 v[140:143], v[100:103], v[172:175], v[140:143]
	v_mfma_f32_16x16x32_bf16 v[124:127], v[90:93], v[180:183], v[124:127]
	v_mfma_f32_16x16x32_bf16 v[116:119], v[100:103], v[180:183], v[116:119]
	v_mfma_f32_16x16x32_bf16 v[78:81], v[90:93], v[188:191], v[78:81]
	v_mfma_f32_16x16x32_bf16 v[74:77], v[100:103], v[188:191], v[74:77]
	v_mfma_f32_16x16x32_bf16 v[160:163], v[94:97], v[168:171], v[160:163]
	v_mfma_f32_16x16x32_bf16 v[156:159], v[104:107], v[168:171], v[156:159]
	v_mfma_f32_16x16x32_bf16 v[144:147], v[94:97], v[176:179], v[144:147]
	v_mfma_f32_16x16x32_bf16 v[140:143], v[104:107], v[176:179], v[140:143]
	v_mfma_f32_16x16x32_bf16 v[124:127], v[94:97], v[184:187], v[124:127]
	v_mfma_f32_16x16x32_bf16 v[116:119], v[104:107], v[184:187], v[116:119]
	v_mfma_f32_16x16x32_bf16 v[78:81], v[94:97], v[192:195], v[78:81]
	v_mfma_f32_16x16x32_bf16 v[74:77], v[104:107], v[192:195], v[74:77]
	v_mfma_f32_16x16x32_bf16 v[152:155], v[108:111], v[164:167], v[152:155]
	v_mfma_f32_16x16x32_bf16 v[148:151], v[120:123], v[164:167], v[148:151]
	v_mfma_f32_16x16x32_bf16 v[136:139], v[108:111], v[172:175], v[136:139]
	v_mfma_f32_16x16x32_bf16 v[132:135], v[120:123], v[172:175], v[132:135]
	v_mfma_f32_16x16x32_bf16 v[86:89], v[108:111], v[180:183], v[86:89]
	v_mfma_f32_16x16x32_bf16 v[82:85], v[120:123], v[180:183], v[82:85]
	v_mfma_f32_16x16x32_bf16 v[70:73], v[108:111], v[188:191], v[70:73]
	v_mfma_f32_16x16x32_bf16 v[66:69], v[120:123], v[188:191], v[66:69]
	v_mfma_f32_16x16x32_bf16 v[152:155], v[112:115], v[168:171], v[152:155]
	v_mfma_f32_16x16x32_bf16 v[148:151], v[128:131], v[168:171], v[148:151]
	v_mfma_f32_16x16x32_bf16 v[136:139], v[112:115], v[176:179], v[136:139]
	v_mfma_f32_16x16x32_bf16 v[132:135], v[128:131], v[176:179], v[132:135]
	v_mfma_f32_16x16x32_bf16 v[86:89], v[112:115], v[184:187], v[86:89]
	v_mfma_f32_16x16x32_bf16 v[82:85], v[128:131], v[184:187], v[82:85]
	v_mfma_f32_16x16x32_bf16 v[70:73], v[112:115], v[192:195], v[70:73]
	v_mfma_f32_16x16x32_bf16 v[66:69], v[128:131], v[192:195], v[66:69]
	s_barrier
	s_add_i32 s4, s6, s91
	v_lshl_add_u64 v[200:201], v[200:201], 0, s[42:43]
	s_mov_b32 m0, s4
	ds_read_b128 v[164:167], v241 offset:49152
	ds_read_b128 v[168:171], v241 offset:50176
	ds_read_b128 v[172:175], v241 offset:51200
	ds_read_b128 v[176:179], v241 offset:52224
	ds_read_b128 v[180:183], v241 offset:53248
	ds_read_b128 v[184:187], v241 offset:54272
	ds_read_b128 v[188:191], v241 offset:55296
	ds_read_b128 v[192:195], v241 offset:56320
	global_load_lds_dwordx4 v[200:201], off
	s_add_i32 m0, s4, 0x2000
	s_add_u32 s4, s74, 0x100080
	v_lshl_add_u64 v[200:201], v[202:203], 0, s[42:43]
	s_addc_u32 s5, s75, 0
	s_add_i32 s6, s7, s91
	global_load_lds_dwordx4 v[200:201], off
	v_lshl_add_u64 v[200:201], s[4:5], 0, v[204:205]
	s_mov_b32 m0, s6
	s_nop 0
	global_load_lds_dwordx4 v[200:201], off
	v_lshl_add_u64 v[200:201], s[4:5], 0, v[208:209]
	s_add_i32 m0, s6, 0x2000
	s_nop 0
	global_load_lds_dwordx4 v[200:201], off
	v_lshl_add_u64 v[200:201], v[210:211], 0, s[42:43]
	s_add_i32 m0, s44, 0x8000
	s_nop 0
	global_load_lds_dwordx4 v[200:201], off
	v_lshl_add_u64 v[200:201], v[212:213], 0, s[42:43]
	s_add_i32 m0, s44, 0xa000
	s_nop 0
	global_load_lds_dwordx4 v[200:201], off
	s_waitcnt vmcnt(8)
	s_waitcnt lgkmcnt(0)
	s_barrier
	v_mfma_f32_16x16x32_bf16 v[62:65], v[90:93], v[164:167], v[62:65]
	v_mfma_f32_16x16x32_bf16 v[58:61], v[100:103], v[164:167], v[58:61]
	v_mfma_f32_16x16x32_bf16 v[46:49], v[90:93], v[172:175], v[46:49]
	v_mfma_f32_16x16x32_bf16 v[42:45], v[100:103], v[172:175], v[42:45]
	v_mfma_f32_16x16x32_bf16 v[30:33], v[90:93], v[180:183], v[30:33]
	v_mfma_f32_16x16x32_bf16 v[26:29], v[100:103], v[180:183], v[26:29]
	v_mfma_f32_16x16x32_bf16 v[14:17], v[90:93], v[188:191], v[14:17]
	v_mfma_f32_16x16x32_bf16 v[10:13], v[100:103], v[188:191], v[10:13]
	v_mfma_f32_16x16x32_bf16 v[62:65], v[94:97], v[168:171], v[62:65]
	v_mfma_f32_16x16x32_bf16 v[58:61], v[104:107], v[168:171], v[58:61]
	v_mfma_f32_16x16x32_bf16 v[46:49], v[94:97], v[176:179], v[46:49]
	v_mfma_f32_16x16x32_bf16 v[42:45], v[104:107], v[176:179], v[42:45]
	v_mfma_f32_16x16x32_bf16 v[30:33], v[94:97], v[184:187], v[30:33]
	v_mfma_f32_16x16x32_bf16 v[26:29], v[104:107], v[184:187], v[26:29]
	v_mfma_f32_16x16x32_bf16 v[14:17], v[94:97], v[192:195], v[14:17]
	v_mfma_f32_16x16x32_bf16 v[10:13], v[104:107], v[192:195], v[10:13]
	v_mfma_f32_16x16x32_bf16 v[54:57], v[108:111], v[164:167], v[54:57]
	v_mfma_f32_16x16x32_bf16 v[50:53], v[120:123], v[164:167], v[50:53]
	v_mfma_f32_16x16x32_bf16 v[38:41], v[108:111], v[172:175], v[38:41]
	v_mfma_f32_16x16x32_bf16 v[34:37], v[120:123], v[172:175], v[34:37]
	v_mfma_f32_16x16x32_bf16 v[22:25], v[108:111], v[180:183], v[22:25]
	v_mfma_f32_16x16x32_bf16 v[18:21], v[120:123], v[180:183], v[18:21]
	v_mfma_f32_16x16x32_bf16 v[6:9], v[108:111], v[188:191], v[6:9]
	v_mfma_f32_16x16x32_bf16 v[2:5], v[120:123], v[188:191], v[2:5]
	v_mfma_f32_16x16x32_bf16 v[54:57], v[112:115], v[168:171], v[54:57]
	v_mfma_f32_16x16x32_bf16 v[50:53], v[128:131], v[168:171], v[50:53]
	v_mfma_f32_16x16x32_bf16 v[38:41], v[112:115], v[176:179], v[38:41]
	v_mfma_f32_16x16x32_bf16 v[34:37], v[128:131], v[176:179], v[34:37]
	v_mfma_f32_16x16x32_bf16 v[22:25], v[112:115], v[184:187], v[22:25]
	v_mfma_f32_16x16x32_bf16 v[18:21], v[128:131], v[184:187], v[18:21]
	v_mfma_f32_16x16x32_bf16 v[6:9], v[112:115], v[192:195], v[6:9]
	v_mfma_f32_16x16x32_bf16 v[2:5], v[128:131], v[192:195], v[2:5]
	s_barrier
	s_mov_b32 s100, 0
	s_add_i32 s95, s95, 2
	s_add_u32 s70, s70, 0x100
	s_addc_u32 s71, s71, 0
	s_add_u32 s69, s69, 0x100
	s_addc_u32 s94, s94, 0
	s_cmp_gt_u32 s95, 61
	s_cbranch_scc0 .LBB0_1172
	s_setprio 0
	s_mov_b32 s100, 1
	s_and_b64 vcc, exec, s[10:11]
	s_cbranch_vccz .LBB0_1175
	s_barrier
